# speedup vs baseline: 1.0009x; 1.0009x over previous
.LBB0_377:
	s_add_u32 s3, s16, 0xfff80080
	s_addc_u32 s18, s17, -1
	s_add_i32 s42, 0, 0x10000
	s_cmp_eq_u32 s41, 28
	s_cselect_b32 s21, s11, s18
	s_cselect_b32 s20, s31, s3
	v_add_u32_e32 v152, s42, v155
	s_cselect_b32 s19, s9, s40
	s_cselect_b32 s18, s34, s35
	s_add_i32 s3, 0, 0x14000
	ds_read_b128 v[140:143], v152
	ds_read_b128 v[144:147], v152 offset:1024
	ds_read_b128 v[148:151], v152 offset:2048
	ds_read_b128 v[158:161], v152 offset:3072
	v_add_u32_e32 v152, s3, v155
	ds_read_b128 v[162:165], v152
	ds_read_b128 v[166:169], v152 offset:1024
	ds_read_b128 v[170:173], v152 offset:2048
	ds_read_b128 v[174:177], v152 offset:3072
	v_lshl_add_u64 v[152:153], s[16:17], 0, v[136:137]
	s_add_i32 m0, s22, 0xc000
	ds_read_b128 v[188:191], v157
	ds_read_b128 v[192:195], v157 offset:1024
	ds_read_b128 v[196:199], v157 offset:2048
	ds_read_b128 v[200:203], v157 offset:3072
	ds_read_b128 v[204:207], v157 offset:4096
	ds_read_b128 v[218:221], v157 offset:5120
	ds_read_b128 v[222:225], v157 offset:6144
	ds_read_b128 v[226:229], v157 offset:7168
	global_load_lds_dwordx4 v[152:153], off
	v_lshl_add_u64 v[152:153], s[16:17], 0, v[138:139]
	s_add_i32 m0, s22, 0xe000
	s_nop 0
	global_load_lds_dwordx4 v[152:153], off
	s_waitcnt vmcnt(8)
	s_waitcnt lgkmcnt(0)
	s_waitcnt lgkmcnt(0)
	v_mfma_f32_16x16x32_bf16 v[126:129], v[140:143], v[188:191], v[126:129]
	v_mfma_f32_16x16x32_bf16 v[122:125], v[148:151], v[188:191], v[122:125]
	s_barrier
	v_mfma_f32_16x16x32_bf16 v[110:113], v[140:143], v[196:199], v[110:113]
	v_mfma_f32_16x16x32_bf16 v[106:109], v[148:151], v[196:199], v[106:109]
	v_mfma_f32_16x16x32_bf16 v[94:97], v[140:143], v[204:207], v[94:97]
	v_mfma_f32_16x16x32_bf16 v[90:93], v[148:151], v[204:207], v[90:93]
	v_mfma_f32_16x16x32_bf16 v[78:81], v[140:143], v[222:225], v[78:81]
	v_mfma_f32_16x16x32_bf16 v[74:77], v[148:151], v[222:225], v[74:77]
	v_mfma_f32_16x16x32_bf16 v[126:129], v[144:147], v[192:195], v[126:129]
	v_mfma_f32_16x16x32_bf16 v[122:125], v[158:161], v[192:195], v[122:125]
	v_mfma_f32_16x16x32_bf16 v[110:113], v[144:147], v[200:203], v[110:113]
	v_mfma_f32_16x16x32_bf16 v[106:109], v[158:161], v[200:203], v[106:109]
	v_mfma_f32_16x16x32_bf16 v[94:97], v[144:147], v[218:221], v[94:97]
	v_mfma_f32_16x16x32_bf16 v[90:93], v[158:161], v[218:221], v[90:93]
	v_mfma_f32_16x16x32_bf16 v[78:81], v[144:147], v[226:229], v[78:81]
	v_mfma_f32_16x16x32_bf16 v[74:77], v[158:161], v[226:229], v[74:77]
	v_mfma_f32_16x16x32_bf16 v[118:121], v[162:165], v[188:191], v[118:121]
	v_mfma_f32_16x16x32_bf16 v[114:117], v[170:173], v[188:191], v[114:117]
	v_mfma_f32_16x16x32_bf16 v[102:105], v[162:165], v[196:199], v[102:105]
	v_mfma_f32_16x16x32_bf16 v[98:101], v[170:173], v[196:199], v[98:101]
	v_mfma_f32_16x16x32_bf16 v[86:89], v[162:165], v[204:207], v[86:89]
	v_mfma_f32_16x16x32_bf16 v[82:85], v[170:173], v[204:207], v[82:85]
	v_mfma_f32_16x16x32_bf16 v[70:73], v[162:165], v[222:225], v[70:73]
	v_mfma_f32_16x16x32_bf16 v[66:69], v[170:173], v[222:225], v[66:69]
	v_mfma_f32_16x16x32_bf16 v[118:121], v[166:169], v[192:195], v[118:121]
	v_mfma_f32_16x16x32_bf16 v[114:117], v[174:177], v[192:195], v[114:117]
	v_mfma_f32_16x16x32_bf16 v[102:105], v[166:169], v[200:203], v[102:105]
	v_mfma_f32_16x16x32_bf16 v[98:101], v[174:177], v[200:203], v[98:101]
	v_mfma_f32_16x16x32_bf16 v[86:89], v[166:169], v[218:221], v[86:89]
	v_mfma_f32_16x16x32_bf16 v[82:85], v[174:177], v[218:221], v[82:85]
	v_mfma_f32_16x16x32_bf16 v[70:73], v[166:169], v[226:229], v[70:73]
	v_mfma_f32_16x16x32_bf16 v[66:69], v[174:177], v[226:229], v[66:69]
	s_barrier
	s_add_i32 s42, s42, s2
	v_lshl_add_u64 v[152:153], s[18:19], 0, v[0:1]
	s_mov_b32 m0, s42
	ds_read_b128 v[188:191], v157 offset:16384
	ds_read_b128 v[192:195], v157 offset:17408
	ds_read_b128 v[196:199], v157 offset:18432
	ds_read_b128 v[200:203], v157 offset:19456
	ds_read_b128 v[204:207], v157 offset:20480
	ds_read_b128 v[218:221], v157 offset:21504
	ds_read_b128 v[222:225], v157 offset:22528
	ds_read_b128 v[226:229], v157 offset:23552
	global_load_lds_dwordx4 v[152:153], off
	s_add_i32 m0, s42, 0x2000
	s_add_u32 s44, s18, 0x80000
	v_lshl_add_u64 v[178:179], s[18:19], 0, v[130:131]
	s_addc_u32 s45, s19, 0
	s_add_i32 s3, s3, s2
	global_load_lds_dwordx4 v[178:179], off
	v_lshl_add_u64 v[180:181], s[44:45], 0, v[0:1]
	s_mov_b32 m0, s3
	v_lshl_add_u64 v[182:183], s[20:21], 0, v[132:133]
	global_load_lds_dwordx4 v[180:181], off
	v_lshl_add_u64 v[180:181], s[44:45], 0, v[130:131]
	s_add_i32 m0, s3, 0x2000
	s_nop 0
	global_load_lds_dwordx4 v[180:181], off
	v_lshl_add_u64 v[180:181], s[20:21], 0, v[134:135]
	s_mov_b32 m0, s22
	s_nop 0
	global_load_lds_dwordx4 v[180:181], off
	s_mov_b32 m0, s23
	s_nop 0
	global_load_lds_dwordx4 v[182:183], off
	s_waitcnt vmcnt(8)
	s_waitcnt lgkmcnt(0)
	s_waitcnt lgkmcnt(0)
	v_mfma_f32_16x16x32_bf16 v[62:65], v[140:143], v[188:191], v[62:65]
	v_mfma_f32_16x16x32_bf16 v[58:61], v[148:151], v[188:191], v[58:61]
	s_barrier
	v_mfma_f32_16x16x32_bf16 v[46:49], v[140:143], v[196:199], v[46:49]
	v_mfma_f32_16x16x32_bf16 v[42:45], v[148:151], v[196:199], v[42:45]
	v_mfma_f32_16x16x32_bf16 v[30:33], v[140:143], v[204:207], v[30:33]
	v_mfma_f32_16x16x32_bf16 v[26:29], v[148:151], v[204:207], v[26:29]
	v_mfma_f32_16x16x32_bf16 v[14:17], v[140:143], v[222:225], v[14:17]
	v_mfma_f32_16x16x32_bf16 v[6:9], v[148:151], v[222:225], v[6:9]
	v_mfma_f32_16x16x32_bf16 v[62:65], v[144:147], v[192:195], v[62:65]
	v_mfma_f32_16x16x32_bf16 v[58:61], v[158:161], v[192:195], v[58:61]
	v_mfma_f32_16x16x32_bf16 v[46:49], v[144:147], v[200:203], v[46:49]
	v_mfma_f32_16x16x32_bf16 v[42:45], v[158:161], v[200:203], v[42:45]
	v_mfma_f32_16x16x32_bf16 v[30:33], v[144:147], v[218:221], v[30:33]
	v_mfma_f32_16x16x32_bf16 v[26:29], v[158:161], v[218:221], v[26:29]
	v_mfma_f32_16x16x32_bf16 v[14:17], v[144:147], v[226:229], v[14:17]
	v_mfma_f32_16x16x32_bf16 v[6:9], v[158:161], v[226:229], v[6:9]
	v_mfma_f32_16x16x32_bf16 v[54:57], v[162:165], v[188:191], v[54:57]
	v_mfma_f32_16x16x32_bf16 v[50:53], v[170:173], v[188:191], v[50:53]
	v_mfma_f32_16x16x32_bf16 v[38:41], v[162:165], v[196:199], v[38:41]
	v_mfma_f32_16x16x32_bf16 v[34:37], v[170:173], v[196:199], v[34:37]
	v_mfma_f32_16x16x32_bf16 v[22:25], v[162:165], v[204:207], v[22:25]
	v_mfma_f32_16x16x32_bf16 v[18:21], v[170:173], v[204:207], v[18:21]
	v_mfma_f32_16x16x32_bf16 v[10:13], v[162:165], v[222:225], v[10:13]
	v_mfma_f32_16x16x32_bf16 v[2:5], v[170:173], v[222:225], v[2:5]
	v_mfma_f32_16x16x32_bf16 v[54:57], v[166:169], v[192:195], v[54:57]
	v_mfma_f32_16x16x32_bf16 v[50:53], v[174:177], v[192:195], v[50:53]
	v_mfma_f32_16x16x32_bf16 v[38:41], v[166:169], v[200:203], v[38:41]
	v_mfma_f32_16x16x32_bf16 v[34:37], v[174:177], v[200:203], v[34:37]
	v_mfma_f32_16x16x32_bf16 v[22:25], v[166:169], v[218:221], v[22:25]
	v_mfma_f32_16x16x32_bf16 v[18:21], v[174:177], v[218:221], v[18:21]
	v_mfma_f32_16x16x32_bf16 v[10:13], v[166:169], v[226:229], v[10:13]
	v_mfma_f32_16x16x32_bf16 v[2:5], v[174:177], v[226:229], v[2:5]
	s_barrier
	s_add_i32 s3, 0, 0x18000
	s_add_i32 s42, 0, 0x1c000
	v_add_u32_e32 v158, s3, v155
	v_add_u32_e32 v174, s42, v155
	ds_read_b128 v[140:143], v158
	ds_read_b128 v[144:147], v158 offset:1024
	ds_read_b128 v[148:151], v158 offset:2048
	ds_read_b128 v[158:161], v158 offset:3072
	ds_read_b128 v[162:165], v174
	ds_read_b128 v[166:169], v174 offset:1024
	ds_read_b128 v[170:173], v174 offset:2048
	ds_read_b128 v[174:177], v174 offset:3072
	s_add_u32 s20, s20, 0x80000
	s_addc_u32 s21, s21, 0
	s_mov_b32 m0, s24
	v_lshl_add_u64 v[184:185], s[20:21], 0, v[134:135]
	ds_read_b128 v[188:191], v157 offset:32768
	ds_read_b128 v[192:195], v157 offset:33792
	ds_read_b128 v[196:199], v157 offset:34816
	ds_read_b128 v[200:203], v157 offset:35840
	ds_read_b128 v[204:207], v157 offset:36864
	ds_read_b128 v[218:221], v157 offset:37888
	ds_read_b128 v[222:225], v157 offset:38912
	ds_read_b128 v[226:229], v157 offset:39936
	global_load_lds_dwordx4 v[184:185], off
	v_lshl_add_u64 v[184:185], s[20:21], 0, v[132:133]
	s_mov_b32 m0, s25
	s_nop 0
	global_load_lds_dwordx4 v[184:185], off
	s_waitcnt vmcnt(8)
	s_waitcnt lgkmcnt(0)
	s_waitcnt lgkmcnt(0)
	v_mfma_f32_16x16x32_bf16 v[126:129], v[140:143], v[188:191], v[126:129]
	v_mfma_f32_16x16x32_bf16 v[122:125], v[148:151], v[188:191], v[122:125]
	s_barrier
	v_mfma_f32_16x16x32_bf16 v[110:113], v[140:143], v[196:199], v[110:113]
	v_mfma_f32_16x16x32_bf16 v[106:109], v[148:151], v[196:199], v[106:109]
	v_mfma_f32_16x16x32_bf16 v[94:97], v[140:143], v[204:207], v[94:97]
	v_mfma_f32_16x16x32_bf16 v[90:93], v[148:151], v[204:207], v[90:93]
	v_mfma_f32_16x16x32_bf16 v[78:81], v[140:143], v[222:225], v[78:81]
	v_mfma_f32_16x16x32_bf16 v[74:77], v[148:151], v[222:225], v[74:77]
	v_mfma_f32_16x16x32_bf16 v[126:129], v[144:147], v[192:195], v[126:129]
	v_mfma_f32_16x16x32_bf16 v[122:125], v[158:161], v[192:195], v[122:125]
	v_mfma_f32_16x16x32_bf16 v[110:113], v[144:147], v[200:203], v[110:113]
	v_mfma_f32_16x16x32_bf16 v[106:109], v[158:161], v[200:203], v[106:109]
	v_mfma_f32_16x16x32_bf16 v[94:97], v[144:147], v[218:221], v[94:97]
	v_mfma_f32_16x16x32_bf16 v[90:93], v[158:161], v[218:221], v[90:93]
	v_mfma_f32_16x16x32_bf16 v[78:81], v[144:147], v[226:229], v[78:81]
	v_mfma_f32_16x16x32_bf16 v[74:77], v[158:161], v[226:229], v[74:77]
	v_mfma_f32_16x16x32_bf16 v[118:121], v[162:165], v[188:191], v[118:121]
	v_mfma_f32_16x16x32_bf16 v[114:117], v[170:173], v[188:191], v[114:117]
	v_mfma_f32_16x16x32_bf16 v[102:105], v[162:165], v[196:199], v[102:105]
	v_mfma_f32_16x16x32_bf16 v[98:101], v[170:173], v[196:199], v[98:101]
	v_mfma_f32_16x16x32_bf16 v[86:89], v[162:165], v[204:207], v[86:89]
	v_mfma_f32_16x16x32_bf16 v[82:85], v[170:173], v[204:207], v[82:85]
	v_mfma_f32_16x16x32_bf16 v[70:73], v[162:165], v[222:225], v[70:73]
	v_mfma_f32_16x16x32_bf16 v[66:69], v[170:173], v[222:225], v[66:69]
	v_mfma_f32_16x16x32_bf16 v[118:121], v[166:169], v[192:195], v[118:121]
	v_mfma_f32_16x16x32_bf16 v[114:117], v[174:177], v[192:195], v[114:117]
	v_mfma_f32_16x16x32_bf16 v[102:105], v[166:169], v[200:203], v[102:105]
	v_mfma_f32_16x16x32_bf16 v[98:101], v[174:177], v[200:203], v[98:101]
	v_mfma_f32_16x16x32_bf16 v[86:89], v[166:169], v[218:221], v[86:89]
	v_mfma_f32_16x16x32_bf16 v[82:85], v[174:177], v[218:221], v[82:85]
	v_mfma_f32_16x16x32_bf16 v[70:73], v[166:169], v[226:229], v[70:73]
	v_mfma_f32_16x16x32_bf16 v[66:69], v[174:177], v[226:229], v[66:69]
	s_barrier
	s_add_i32 s3, s3, s2
	v_lshl_add_u64 v[152:153], v[152:153], 0, s[52:53]
	s_mov_b32 m0, s3
	ds_read_b128 v[188:191], v157 offset:49152
	ds_read_b128 v[192:195], v157 offset:50176
	ds_read_b128 v[196:199], v157 offset:51200
	ds_read_b128 v[200:203], v157 offset:52224
	ds_read_b128 v[204:207], v157 offset:53248
	ds_read_b128 v[218:221], v157 offset:54272
	ds_read_b128 v[222:225], v157 offset:55296
	ds_read_b128 v[226:229], v157 offset:56320
	global_load_lds_dwordx4 v[152:153], off
	s_add_i32 m0, s3, 0x2000
	s_add_u32 s18, s18, 0x80080
	v_lshl_add_u64 v[152:153], v[178:179], 0, s[52:53]
	s_addc_u32 s19, s19, 0
	s_add_i32 s3, s42, s2
	global_load_lds_dwordx4 v[152:153], off
	v_lshl_add_u64 v[152:153], s[18:19], 0, v[0:1]
	s_mov_b32 m0, s3
	s_nop 0
	global_load_lds_dwordx4 v[152:153], off
	v_lshl_add_u64 v[152:153], s[18:19], 0, v[130:131]
	s_add_i32 m0, s3, 0x2000
	s_nop 0
	global_load_lds_dwordx4 v[152:153], off
	v_lshl_add_u64 v[152:153], v[180:181], 0, s[52:53]
	s_mov_b32 m0, s26
	s_nop 0
	global_load_lds_dwordx4 v[152:153], off
	v_lshl_add_u64 v[152:153], v[182:183], 0, s[52:53]
	s_mov_b32 m0, s27
	s_nop 0
	global_load_lds_dwordx4 v[152:153], off
	s_waitcnt vmcnt(8)
	s_waitcnt lgkmcnt(0)
	s_waitcnt lgkmcnt(0)
	v_mfma_f32_16x16x32_bf16 v[62:65], v[140:143], v[188:191], v[62:65]
	v_mfma_f32_16x16x32_bf16 v[58:61], v[148:151], v[188:191], v[58:61]
	s_barrier
	v_mfma_f32_16x16x32_bf16 v[46:49], v[140:143], v[196:199], v[46:49]
	v_mfma_f32_16x16x32_bf16 v[42:45], v[148:151], v[196:199], v[42:45]
	v_mfma_f32_16x16x32_bf16 v[30:33], v[140:143], v[204:207], v[30:33]
	v_mfma_f32_16x16x32_bf16 v[26:29], v[148:151], v[204:207], v[26:29]
	v_mfma_f32_16x16x32_bf16 v[14:17], v[140:143], v[222:225], v[14:17]
	v_mfma_f32_16x16x32_bf16 v[6:9], v[148:151], v[222:225], v[6:9]
	v_mfma_f32_16x16x32_bf16 v[62:65], v[144:147], v[192:195], v[62:65]
	v_mfma_f32_16x16x32_bf16 v[58:61], v[158:161], v[192:195], v[58:61]
	v_mfma_f32_16x16x32_bf16 v[46:49], v[144:147], v[200:203], v[46:49]
	v_mfma_f32_16x16x32_bf16 v[42:45], v[158:161], v[200:203], v[42:45]
	v_mfma_f32_16x16x32_bf16 v[30:33], v[144:147], v[218:221], v[30:33]
	v_mfma_f32_16x16x32_bf16 v[26:29], v[158:161], v[218:221], v[26:29]
	v_mfma_f32_16x16x32_bf16 v[14:17], v[144:147], v[226:229], v[14:17]
	v_mfma_f32_16x16x32_bf16 v[6:9], v[158:161], v[226:229], v[6:9]
	v_mfma_f32_16x16x32_bf16 v[54:57], v[162:165], v[188:191], v[54:57]
	v_mfma_f32_16x16x32_bf16 v[50:53], v[170:173], v[188:191], v[50:53]
	v_mfma_f32_16x16x32_bf16 v[38:41], v[162:165], v[196:199], v[38:41]
	v_mfma_f32_16x16x32_bf16 v[34:37], v[170:173], v[196:199], v[34:37]
	v_mfma_f32_16x16x32_bf16 v[22:25], v[162:165], v[204:207], v[22:25]
	v_mfma_f32_16x16x32_bf16 v[18:21], v[170:173], v[204:207], v[18:21]
	v_mfma_f32_16x16x32_bf16 v[10:13], v[162:165], v[222:225], v[10:13]
	v_mfma_f32_16x16x32_bf16 v[2:5], v[170:173], v[222:225], v[2:5]
	v_mfma_f32_16x16x32_bf16 v[54:57], v[166:169], v[192:195], v[54:57]
	v_mfma_f32_16x16x32_bf16 v[50:53], v[174:177], v[192:195], v[50:53]
	v_mfma_f32_16x16x32_bf16 v[38:41], v[166:169], v[200:203], v[38:41]
	v_mfma_f32_16x16x32_bf16 v[34:37], v[174:177], v[200:203], v[34:37]
	v_mfma_f32_16x16x32_bf16 v[22:25], v[166:169], v[218:221], v[22:25]
	v_mfma_f32_16x16x32_bf16 v[18:21], v[174:177], v[218:221], v[18:21]
	v_mfma_f32_16x16x32_bf16 v[10:13], v[166:169], v[226:229], v[10:13]
	v_mfma_f32_16x16x32_bf16 v[2:5], v[174:177], v[226:229], v[2:5]
	s_barrier
	s_add_i32 s41, s41, 2
	s_add_u32 s16, s16, 0x100
	s_addc_u32 s17, s17, 0
	s_add_u32 s35, s35, 0x100
	s_addc_u32 s40, s40, 0
	s_cmp_gt_u32 s41, 29
	s_cbranch_scc0 .LBB0_377
	s_and_b64 vcc, exec, s[6:7]
	s_movk_i32 s40, 0x4000
	s_movk_i32 s41, 0x6000
	s_cbranch_vccz .LBB0_380
	s_barrier

.LBB0_399:
	s_add_u32 s3, s0, 0xfff80080
	s_addc_u32 s4, s1, -1
	s_add_i32 s42, 0, 0x10000
	s_cmp_eq_u32 s46, 28
	s_cselect_b32 s7, s8, s4
	s_cselect_b32 s6, s9, s3
	v_add_u32_e32 v0, s42, v206
	s_cselect_b32 s5, s19, s27
	s_cselect_b32 s4, s21, s26
	s_add_i32 s3, 0, 0x14000
	ds_read_b128 v[130:133], v0
	ds_read_b128 v[134:137], v0 offset:1024
	ds_read_b128 v[138:141], v0 offset:2048
	ds_read_b128 v[142:145], v0 offset:3072
	v_add_u32_e32 v0, s3, v206
	ds_read_b128 v[146:149], v0
	ds_read_b128 v[150:153], v0 offset:1024
	s_waitcnt lgkmcnt(0)
	ds_read_b128 v[154:157], v0 offset:2048
	ds_read_b128 v[158:161], v0 offset:3072
	v_lshl_add_u64 v[176:177], s[0:1], 0, v[170:171]
	s_add_i32 m0, s28, 0xc000
	ds_read_b128 v[196:199], v218
	ds_read_b128 v[200:203], v218 offset:1024
	ds_read_b128 v[220:223], v218 offset:2048
	ds_read_b128 v[224:227], v218 offset:3072
	ds_read_b128 v[228:231], v218 offset:4096
	ds_read_b128 v[232:235], v218 offset:5120
	ds_read_b128 v[236:239], v218 offset:6144
	ds_read_b128 v[240:243], v218 offset:7168
	global_load_lds_dwordx4 v[176:177], off
	v_lshl_add_u64 v[176:177], s[0:1], 0, v[172:173]
	s_add_i32 m0, s28, 0xe000
	s_nop 0
	global_load_lds_dwordx4 v[176:177], off
	s_waitcnt vmcnt(8)
	s_waitcnt lgkmcnt(0)
	s_waitcnt lgkmcnt(0)
	v_mfma_f32_16x16x32_bf16 v[126:129], v[130:133], v[196:199], v[126:129]
	v_mfma_f32_16x16x32_bf16 v[122:125], v[138:141], v[196:199], v[122:125]
	s_barrier
	v_mfma_f32_16x16x32_bf16 v[118:121], v[130:133], v[220:223], v[118:121]
	v_mfma_f32_16x16x32_bf16 v[114:117], v[138:141], v[220:223], v[114:117]
	v_mfma_f32_16x16x32_bf16 v[110:113], v[130:133], v[228:231], v[110:113]
	v_mfma_f32_16x16x32_bf16 v[106:109], v[138:141], v[228:231], v[106:109]
	v_mfma_f32_16x16x32_bf16 v[102:105], v[130:133], v[236:239], v[102:105]
	v_mfma_f32_16x16x32_bf16 v[98:101], v[138:141], v[236:239], v[98:101]
	v_mfma_f32_16x16x32_bf16 v[126:129], v[134:137], v[200:203], v[126:129]
	v_mfma_f32_16x16x32_bf16 v[122:125], v[142:145], v[200:203], v[122:125]
	v_mfma_f32_16x16x32_bf16 v[118:121], v[134:137], v[224:227], v[118:121]
	v_mfma_f32_16x16x32_bf16 v[114:117], v[142:145], v[224:227], v[114:117]
	v_mfma_f32_16x16x32_bf16 v[110:113], v[134:137], v[232:235], v[110:113]
	v_mfma_f32_16x16x32_bf16 v[106:109], v[142:145], v[232:235], v[106:109]
	v_mfma_f32_16x16x32_bf16 v[102:105], v[134:137], v[240:243], v[102:105]
	v_mfma_f32_16x16x32_bf16 v[98:101], v[142:145], v[240:243], v[98:101]
	v_mfma_f32_16x16x32_bf16 v[94:97], v[146:149], v[196:199], v[94:97]
	v_mfma_f32_16x16x32_bf16 v[90:93], v[154:157], v[196:199], v[90:93]
	v_mfma_f32_16x16x32_bf16 v[86:89], v[146:149], v[220:223], v[86:89]
	v_mfma_f32_16x16x32_bf16 v[82:85], v[154:157], v[220:223], v[82:85]
	v_mfma_f32_16x16x32_bf16 v[78:81], v[146:149], v[228:231], v[78:81]
	v_mfma_f32_16x16x32_bf16 v[74:77], v[154:157], v[228:231], v[74:77]
	v_mfma_f32_16x16x32_bf16 v[70:73], v[146:149], v[236:239], v[70:73]
	v_mfma_f32_16x16x32_bf16 v[66:69], v[154:157], v[236:239], v[66:69]
	v_mfma_f32_16x16x32_bf16 v[94:97], v[150:153], v[200:203], v[94:97]
	v_mfma_f32_16x16x32_bf16 v[90:93], v[158:161], v[200:203], v[90:93]
	v_mfma_f32_16x16x32_bf16 v[86:89], v[150:153], v[224:227], v[86:89]
	v_mfma_f32_16x16x32_bf16 v[82:85], v[158:161], v[224:227], v[82:85]
	v_mfma_f32_16x16x32_bf16 v[78:81], v[150:153], v[232:235], v[78:81]
	v_mfma_f32_16x16x32_bf16 v[74:77], v[158:161], v[232:235], v[74:77]
	v_mfma_f32_16x16x32_bf16 v[70:73], v[150:153], v[240:243], v[70:73]
	v_mfma_f32_16x16x32_bf16 v[66:69], v[158:161], v[240:243], v[66:69]
	s_barrier
	s_add_i32 s42, s42, s2
	v_lshl_add_u64 v[176:177], s[4:5], 0, v[166:167]
	s_mov_b32 m0, s42
	ds_read_b128 v[196:199], v218 offset:16384
	ds_read_b128 v[200:203], v218 offset:17408
	ds_read_b128 v[220:223], v218 offset:18432
	ds_read_b128 v[224:227], v218 offset:19456
	ds_read_b128 v[228:231], v218 offset:20480
	ds_read_b128 v[232:235], v218 offset:21504
	ds_read_b128 v[236:239], v218 offset:22528
	ds_read_b128 v[240:243], v218 offset:23552
	global_load_lds_dwordx4 v[176:177], off
	s_add_i32 m0, s42, 0x2000
	s_add_u32 s56, s4, 0x80000
	v_lshl_add_u64 v[178:179], s[4:5], 0, v[162:163]
	s_addc_u32 s57, s5, 0
	s_add_i32 s3, s3, s2
	global_load_lds_dwordx4 v[178:179], off
	v_lshl_add_u64 v[244:245], s[56:57], 0, v[166:167]
	s_mov_b32 m0, s3
	v_lshl_add_u64 v[246:247], s[6:7], 0, v[164:165]
	global_load_lds_dwordx4 v[244:245], off
	v_lshl_add_u64 v[244:245], s[56:57], 0, v[162:163]
	s_add_i32 m0, s3, 0x2000
	s_nop 0
	global_load_lds_dwordx4 v[244:245], off
	v_lshl_add_u64 v[244:245], s[6:7], 0, v[168:169]
	s_mov_b32 m0, s28
	s_nop 0
	global_load_lds_dwordx4 v[244:245], off
	s_mov_b32 m0, s29
	s_nop 0
	global_load_lds_dwordx4 v[246:247], off
	s_waitcnt vmcnt(8)
	s_waitcnt lgkmcnt(0)
	s_waitcnt lgkmcnt(0)
	v_mfma_f32_16x16x32_bf16 v[62:65], v[130:133], v[196:199], v[62:65]
	v_mfma_f32_16x16x32_bf16 v[58:61], v[138:141], v[196:199], v[58:61]
	s_barrier
	v_mfma_f32_16x16x32_bf16 v[54:57], v[130:133], v[220:223], v[54:57]
	v_mfma_f32_16x16x32_bf16 v[50:53], v[138:141], v[220:223], v[50:53]
	v_mfma_f32_16x16x32_bf16 v[46:49], v[130:133], v[228:231], v[46:49]
	v_mfma_f32_16x16x32_bf16 v[42:45], v[138:141], v[228:231], v[42:45]
	v_mfma_f32_16x16x32_bf16 v[38:41], v[130:133], v[236:239], v[38:41]
	v_mfma_f32_16x16x32_bf16 v[34:37], v[138:141], v[236:239], v[34:37]
	v_mfma_f32_16x16x32_bf16 v[62:65], v[134:137], v[200:203], v[62:65]
	v_mfma_f32_16x16x32_bf16 v[58:61], v[142:145], v[200:203], v[58:61]
	v_mfma_f32_16x16x32_bf16 v[54:57], v[134:137], v[224:227], v[54:57]
	v_mfma_f32_16x16x32_bf16 v[50:53], v[142:145], v[224:227], v[50:53]
	v_mfma_f32_16x16x32_bf16 v[46:49], v[134:137], v[232:235], v[46:49]
	v_mfma_f32_16x16x32_bf16 v[42:45], v[142:145], v[232:235], v[42:45]
	v_mfma_f32_16x16x32_bf16 v[38:41], v[134:137], v[240:243], v[38:41]
	v_mfma_f32_16x16x32_bf16 v[34:37], v[142:145], v[240:243], v[34:37]
	v_mfma_f32_16x16x32_bf16 v[30:33], v[146:149], v[196:199], v[30:33]
	v_mfma_f32_16x16x32_bf16 v[26:29], v[154:157], v[196:199], v[26:29]
	v_mfma_f32_16x16x32_bf16 v[22:25], v[146:149], v[220:223], v[22:25]
	v_mfma_f32_16x16x32_bf16 v[18:21], v[154:157], v[220:223], v[18:21]
	v_mfma_f32_16x16x32_bf16 v[14:17], v[146:149], v[228:231], v[14:17]
	v_mfma_f32_16x16x32_bf16 v[10:13], v[154:157], v[228:231], v[10:13]
	v_mfma_f32_16x16x32_bf16 v[6:9], v[146:149], v[236:239], v[6:9]
	v_mfma_f32_16x16x32_bf16 v[2:5], v[154:157], v[236:239], v[2:5]
	v_mfma_f32_16x16x32_bf16 v[30:33], v[150:153], v[200:203], v[30:33]
	v_mfma_f32_16x16x32_bf16 v[26:29], v[158:161], v[200:203], v[26:29]
	v_mfma_f32_16x16x32_bf16 v[22:25], v[150:153], v[224:227], v[22:25]
	v_mfma_f32_16x16x32_bf16 v[18:21], v[158:161], v[224:227], v[18:21]
	v_mfma_f32_16x16x32_bf16 v[14:17], v[150:153], v[232:235], v[14:17]
	v_mfma_f32_16x16x32_bf16 v[10:13], v[158:161], v[232:235], v[10:13]
	v_mfma_f32_16x16x32_bf16 v[6:9], v[150:153], v[240:243], v[6:9]
	v_mfma_f32_16x16x32_bf16 v[2:5], v[158:161], v[240:243], v[2:5]
	s_barrier
	s_add_i32 s3, 0, 0x18000
	v_add_u32_e32 v0, s3, v206
	s_add_i32 s42, 0, 0x1c000
	ds_read_b128 v[130:133], v0
	ds_read_b128 v[134:137], v0 offset:1024
	ds_read_b128 v[138:141], v0 offset:2048
	ds_read_b128 v[142:145], v0 offset:3072
	v_add_u32_e32 v0, s42, v206
	ds_read_b128 v[146:149], v0
	ds_read_b128 v[150:153], v0 offset:1024
	ds_read_b128 v[154:157], v0 offset:2048
	ds_read_b128 v[158:161], v0 offset:3072
	s_add_u32 s6, s6, 0x80000
	s_addc_u32 s7, s7, 0
	s_mov_b32 m0, s30
	v_lshl_add_u64 v[248:249], s[6:7], 0, v[168:169]
	ds_read_b128 v[196:199], v218 offset:32768
	ds_read_b128 v[200:203], v218 offset:33792
	ds_read_b128 v[220:223], v218 offset:34816
	ds_read_b128 v[224:227], v218 offset:35840
	ds_read_b128 v[228:231], v218 offset:36864
	ds_read_b128 v[232:235], v218 offset:37888
	ds_read_b128 v[236:239], v218 offset:38912
	ds_read_b128 v[240:243], v218 offset:39936
	global_load_lds_dwordx4 v[248:249], off
	v_lshl_add_u64 v[248:249], s[6:7], 0, v[164:165]
	s_mov_b32 m0, s31
	s_nop 0
	global_load_lds_dwordx4 v[248:249], off
	s_waitcnt vmcnt(8)
	s_waitcnt lgkmcnt(0)
	s_waitcnt lgkmcnt(0)
	v_mfma_f32_16x16x32_bf16 v[126:129], v[130:133], v[196:199], v[126:129]
	v_mfma_f32_16x16x32_bf16 v[122:125], v[138:141], v[196:199], v[122:125]
	s_barrier
	v_mfma_f32_16x16x32_bf16 v[118:121], v[130:133], v[220:223], v[118:121]
	v_mfma_f32_16x16x32_bf16 v[114:117], v[138:141], v[220:223], v[114:117]
	v_mfma_f32_16x16x32_bf16 v[110:113], v[130:133], v[228:231], v[110:113]
	v_mfma_f32_16x16x32_bf16 v[106:109], v[138:141], v[228:231], v[106:109]
	v_mfma_f32_16x16x32_bf16 v[102:105], v[130:133], v[236:239], v[102:105]
	v_mfma_f32_16x16x32_bf16 v[98:101], v[138:141], v[236:239], v[98:101]
	v_mfma_f32_16x16x32_bf16 v[126:129], v[134:137], v[200:203], v[126:129]
	v_mfma_f32_16x16x32_bf16 v[122:125], v[142:145], v[200:203], v[122:125]
	v_mfma_f32_16x16x32_bf16 v[118:121], v[134:137], v[224:227], v[118:121]
	v_mfma_f32_16x16x32_bf16 v[114:117], v[142:145], v[224:227], v[114:117]
	v_mfma_f32_16x16x32_bf16 v[110:113], v[134:137], v[232:235], v[110:113]
	v_mfma_f32_16x16x32_bf16 v[106:109], v[142:145], v[232:235], v[106:109]
	v_mfma_f32_16x16x32_bf16 v[102:105], v[134:137], v[240:243], v[102:105]
	v_mfma_f32_16x16x32_bf16 v[98:101], v[142:145], v[240:243], v[98:101]
	v_mfma_f32_16x16x32_bf16 v[94:97], v[146:149], v[196:199], v[94:97]
	v_mfma_f32_16x16x32_bf16 v[90:93], v[154:157], v[196:199], v[90:93]
	v_mfma_f32_16x16x32_bf16 v[86:89], v[146:149], v[220:223], v[86:89]
	v_mfma_f32_16x16x32_bf16 v[82:85], v[154:157], v[220:223], v[82:85]
	v_mfma_f32_16x16x32_bf16 v[78:81], v[146:149], v[228:231], v[78:81]
	v_mfma_f32_16x16x32_bf16 v[74:77], v[154:157], v[228:231], v[74:77]
	v_mfma_f32_16x16x32_bf16 v[70:73], v[146:149], v[236:239], v[70:73]
	v_mfma_f32_16x16x32_bf16 v[66:69], v[154:157], v[236:239], v[66:69]
	v_mfma_f32_16x16x32_bf16 v[94:97], v[150:153], v[200:203], v[94:97]
	v_mfma_f32_16x16x32_bf16 v[90:93], v[158:161], v[200:203], v[90:93]
	v_mfma_f32_16x16x32_bf16 v[86:89], v[150:153], v[224:227], v[86:89]
	v_mfma_f32_16x16x32_bf16 v[82:85], v[158:161], v[224:227], v[82:85]
	v_mfma_f32_16x16x32_bf16 v[78:81], v[150:153], v[232:235], v[78:81]
	v_mfma_f32_16x16x32_bf16 v[74:77], v[158:161], v[232:235], v[74:77]
	v_mfma_f32_16x16x32_bf16 v[70:73], v[150:153], v[240:243], v[70:73]
	v_mfma_f32_16x16x32_bf16 v[66:69], v[158:161], v[240:243], v[66:69]
	s_barrier
	s_add_i32 s3, s3, s2
	v_lshl_add_u64 v[176:177], v[176:177], 0, s[52:53]
	s_mov_b32 m0, s3
	ds_read_b128 v[196:199], v218 offset:49152
	ds_read_b128 v[200:203], v218 offset:50176
	ds_read_b128 v[220:223], v218 offset:51200
	ds_read_b128 v[224:227], v218 offset:52224
	ds_read_b128 v[228:231], v218 offset:53248
	ds_read_b128 v[232:235], v218 offset:54272
	ds_read_b128 v[236:239], v218 offset:55296
	ds_read_b128 v[240:243], v218 offset:56320
	global_load_lds_dwordx4 v[176:177], off
	s_add_i32 m0, s3, 0x2000
	s_add_u32 s4, s4, 0x80080
	v_lshl_add_u64 v[176:177], v[178:179], 0, s[52:53]
	s_addc_u32 s5, s5, 0
	s_add_i32 s3, s42, s2
	global_load_lds_dwordx4 v[176:177], off
	v_lshl_add_u64 v[176:177], s[4:5], 0, v[166:167]
	s_mov_b32 m0, s3
	s_nop 0
	global_load_lds_dwordx4 v[176:177], off
	v_lshl_add_u64 v[176:177], s[4:5], 0, v[162:163]
	s_add_i32 m0, s3, 0x2000
	s_nop 0
	global_load_lds_dwordx4 v[176:177], off
	v_lshl_add_u64 v[176:177], v[244:245], 0, s[52:53]
	s_mov_b32 m0, s35
	s_nop 0
	global_load_lds_dwordx4 v[176:177], off
	v_lshl_add_u64 v[176:177], v[246:247], 0, s[52:53]
	s_mov_b32 m0, s40
	s_nop 0
	global_load_lds_dwordx4 v[176:177], off
	s_waitcnt vmcnt(8)
	s_waitcnt lgkmcnt(0)
	s_waitcnt lgkmcnt(0)
	v_mfma_f32_16x16x32_bf16 v[62:65], v[130:133], v[196:199], v[62:65]
	v_mfma_f32_16x16x32_bf16 v[58:61], v[138:141], v[196:199], v[58:61]
	s_barrier
	v_mfma_f32_16x16x32_bf16 v[54:57], v[130:133], v[220:223], v[54:57]
	v_mfma_f32_16x16x32_bf16 v[50:53], v[138:141], v[220:223], v[50:53]
	v_mfma_f32_16x16x32_bf16 v[46:49], v[130:133], v[228:231], v[46:49]
	v_mfma_f32_16x16x32_bf16 v[42:45], v[138:141], v[228:231], v[42:45]
	v_mfma_f32_16x16x32_bf16 v[38:41], v[130:133], v[236:239], v[38:41]
	v_mfma_f32_16x16x32_bf16 v[34:37], v[138:141], v[236:239], v[34:37]
	v_mfma_f32_16x16x32_bf16 v[62:65], v[134:137], v[200:203], v[62:65]
	v_mfma_f32_16x16x32_bf16 v[58:61], v[142:145], v[200:203], v[58:61]
	v_mfma_f32_16x16x32_bf16 v[54:57], v[134:137], v[224:227], v[54:57]
	v_mfma_f32_16x16x32_bf16 v[50:53], v[142:145], v[224:227], v[50:53]
	v_mfma_f32_16x16x32_bf16 v[46:49], v[134:137], v[232:235], v[46:49]
	v_mfma_f32_16x16x32_bf16 v[42:45], v[142:145], v[232:235], v[42:45]
	v_mfma_f32_16x16x32_bf16 v[38:41], v[134:137], v[240:243], v[38:41]
	v_mfma_f32_16x16x32_bf16 v[34:37], v[142:145], v[240:243], v[34:37]
	v_mfma_f32_16x16x32_bf16 v[30:33], v[146:149], v[196:199], v[30:33]
	v_mfma_f32_16x16x32_bf16 v[26:29], v[154:157], v[196:199], v[26:29]
	v_mfma_f32_16x16x32_bf16 v[22:25], v[146:149], v[220:223], v[22:25]
	v_mfma_f32_16x16x32_bf16 v[18:21], v[154:157], v[220:223], v[18:21]
	v_mfma_f32_16x16x32_bf16 v[14:17], v[146:149], v[228:231], v[14:17]
	v_mfma_f32_16x16x32_bf16 v[10:13], v[154:157], v[228:231], v[10:13]
	v_mfma_f32_16x16x32_bf16 v[6:9], v[146:149], v[236:239], v[6:9]
	v_mfma_f32_16x16x32_bf16 v[2:5], v[154:157], v[236:239], v[2:5]
	v_mfma_f32_16x16x32_bf16 v[30:33], v[150:153], v[200:203], v[30:33]
	v_mfma_f32_16x16x32_bf16 v[26:29], v[158:161], v[200:203], v[26:29]
	v_mfma_f32_16x16x32_bf16 v[22:25], v[150:153], v[224:227], v[22:25]
	v_mfma_f32_16x16x32_bf16 v[18:21], v[158:161], v[224:227], v[18:21]
	v_mfma_f32_16x16x32_bf16 v[14:17], v[150:153], v[232:235], v[14:17]
	v_mfma_f32_16x16x32_bf16 v[10:13], v[158:161], v[232:235], v[10:13]
	v_mfma_f32_16x16x32_bf16 v[6:9], v[150:153], v[240:243], v[6:9]
	v_mfma_f32_16x16x32_bf16 v[2:5], v[158:161], v[240:243], v[2:5]
	s_barrier
	s_add_i32 s46, s46, 2
	s_add_u32 s0, s0, 0x100
	s_addc_u32 s1, s1, 0
	s_add_u32 s26, s26, 0x100
	s_addc_u32 s27, s27, 0
	s_cmp_gt_u32 s46, 29
	s_cbranch_scc0 .LBB0_399
	s_and_b64 vcc, exec, s[14:15]
	s_cbranch_vccz .LBB0_402
	s_barrier

.LBB0_846:
	s_add_u32 s3, s0, 0xfff80080
	s_addc_u32 s18, s1, -1
	s_add_i32 s42, 0, 0x10000
	s_cmp_eq_u32 s41, 28
	s_cselect_b32 s21, s13, s18
	s_cselect_b32 s20, s31, s3
	s_cselect_b32 s19, s11, s40
	s_cselect_b32 s18, s34, s35
	s_add_i32 s3, 0, 0x14000
	v_add_u32_e32 v152, s42, v163
	v_add_u32_e32 v160, s3, v163
	ds_read_b128 v[140:143], v152
	ds_read_b128 v[144:147], v152 offset:1024
	ds_read_b128 v[148:151], v152 offset:2048
	ds_read_b128 v[152:155], v152 offset:3072
	ds_read_b128 v[156:159], v160
	ds_read_b128 v[166:169], v160 offset:1024
	ds_read_b128 v[170:173], v160 offset:2048
	ds_read_b128 v[174:177], v160 offset:3072
	v_lshl_add_u64 v[160:161], s[0:1], 0, v[136:137]
	s_add_i32 m0, s22, 0xc000
	ds_read_b128 v[188:191], v165
	ds_read_b128 v[192:195], v165 offset:1024
	ds_read_b128 v[196:199], v165 offset:2048
	ds_read_b128 v[200:203], v165 offset:3072
	ds_read_b128 v[204:207], v165 offset:4096
	ds_read_b128 v[218:221], v165 offset:5120
	ds_read_b128 v[222:225], v165 offset:6144
	ds_read_b128 v[226:229], v165 offset:7168
	global_load_lds_dwordx4 v[160:161], off
	v_lshl_add_u64 v[160:161], s[0:1], 0, v[138:139]
	s_add_i32 m0, s22, 0xe000
	s_nop 0
	global_load_lds_dwordx4 v[160:161], off
	s_waitcnt vmcnt(8)
	s_waitcnt lgkmcnt(0)
	s_waitcnt lgkmcnt(0)
	v_mfma_f32_16x16x32_bf16 v[126:129], v[140:143], v[188:191], v[126:129]
	v_mfma_f32_16x16x32_bf16 v[122:125], v[148:151], v[188:191], v[122:125]
	s_barrier
	v_mfma_f32_16x16x32_bf16 v[110:113], v[140:143], v[196:199], v[110:113]
	v_mfma_f32_16x16x32_bf16 v[106:109], v[148:151], v[196:199], v[106:109]
	v_mfma_f32_16x16x32_bf16 v[94:97], v[140:143], v[204:207], v[94:97]
	v_mfma_f32_16x16x32_bf16 v[90:93], v[148:151], v[204:207], v[90:93]
	v_mfma_f32_16x16x32_bf16 v[78:81], v[140:143], v[222:225], v[78:81]
	v_mfma_f32_16x16x32_bf16 v[74:77], v[148:151], v[222:225], v[74:77]
	v_mfma_f32_16x16x32_bf16 v[126:129], v[144:147], v[192:195], v[126:129]
	v_mfma_f32_16x16x32_bf16 v[122:125], v[152:155], v[192:195], v[122:125]
	v_mfma_f32_16x16x32_bf16 v[110:113], v[144:147], v[200:203], v[110:113]
	v_mfma_f32_16x16x32_bf16 v[106:109], v[152:155], v[200:203], v[106:109]
	v_mfma_f32_16x16x32_bf16 v[94:97], v[144:147], v[218:221], v[94:97]
	v_mfma_f32_16x16x32_bf16 v[90:93], v[152:155], v[218:221], v[90:93]
	v_mfma_f32_16x16x32_bf16 v[78:81], v[144:147], v[226:229], v[78:81]
	v_mfma_f32_16x16x32_bf16 v[74:77], v[152:155], v[226:229], v[74:77]
	v_mfma_f32_16x16x32_bf16 v[118:121], v[156:159], v[188:191], v[118:121]
	v_mfma_f32_16x16x32_bf16 v[114:117], v[170:173], v[188:191], v[114:117]
	v_mfma_f32_16x16x32_bf16 v[102:105], v[156:159], v[196:199], v[102:105]
	v_mfma_f32_16x16x32_bf16 v[98:101], v[170:173], v[196:199], v[98:101]
	v_mfma_f32_16x16x32_bf16 v[86:89], v[156:159], v[204:207], v[86:89]
	v_mfma_f32_16x16x32_bf16 v[82:85], v[170:173], v[204:207], v[82:85]
	v_mfma_f32_16x16x32_bf16 v[70:73], v[156:159], v[222:225], v[70:73]
	v_mfma_f32_16x16x32_bf16 v[66:69], v[170:173], v[222:225], v[66:69]
	v_mfma_f32_16x16x32_bf16 v[118:121], v[166:169], v[192:195], v[118:121]
	v_mfma_f32_16x16x32_bf16 v[114:117], v[174:177], v[192:195], v[114:117]
	v_mfma_f32_16x16x32_bf16 v[102:105], v[166:169], v[200:203], v[102:105]
	v_mfma_f32_16x16x32_bf16 v[98:101], v[174:177], v[200:203], v[98:101]
	v_mfma_f32_16x16x32_bf16 v[86:89], v[166:169], v[218:221], v[86:89]
	v_mfma_f32_16x16x32_bf16 v[82:85], v[174:177], v[218:221], v[82:85]
	v_mfma_f32_16x16x32_bf16 v[70:73], v[166:169], v[226:229], v[70:73]
	v_mfma_f32_16x16x32_bf16 v[66:69], v[174:177], v[226:229], v[66:69]
	s_barrier
	s_add_i32 s42, s42, s2
	v_lshl_add_u64 v[160:161], s[18:19], 0, v[0:1]
	s_mov_b32 m0, s42
	ds_read_b128 v[188:191], v165 offset:16384
	ds_read_b128 v[192:195], v165 offset:17408
	ds_read_b128 v[196:199], v165 offset:18432
	ds_read_b128 v[200:203], v165 offset:19456
	ds_read_b128 v[204:207], v165 offset:20480
	ds_read_b128 v[218:221], v165 offset:21504
	ds_read_b128 v[222:225], v165 offset:22528
	ds_read_b128 v[226:229], v165 offset:23552
	global_load_lds_dwordx4 v[160:161], off
	s_add_i32 m0, s42, 0x2000
	s_add_u32 s44, s18, 0x80000
	v_lshl_add_u64 v[178:179], s[18:19], 0, v[130:131]
	s_addc_u32 s45, s19, 0
	s_add_i32 s3, s3, s2
	global_load_lds_dwordx4 v[178:179], off
	v_lshl_add_u64 v[180:181], s[44:45], 0, v[0:1]
	s_mov_b32 m0, s3
	v_lshl_add_u64 v[182:183], s[20:21], 0, v[132:133]
	global_load_lds_dwordx4 v[180:181], off
	v_lshl_add_u64 v[180:181], s[44:45], 0, v[130:131]
	s_add_i32 m0, s3, 0x2000
	s_nop 0
	global_load_lds_dwordx4 v[180:181], off
	v_lshl_add_u64 v[180:181], s[20:21], 0, v[134:135]
	s_mov_b32 m0, s22
	s_nop 0
	global_load_lds_dwordx4 v[180:181], off
	s_mov_b32 m0, s23
	s_nop 0
	global_load_lds_dwordx4 v[182:183], off
	s_waitcnt vmcnt(8)
	s_waitcnt lgkmcnt(0)
	s_waitcnt lgkmcnt(0)
	v_mfma_f32_16x16x32_bf16 v[62:65], v[140:143], v[188:191], v[62:65]
	v_mfma_f32_16x16x32_bf16 v[58:61], v[148:151], v[188:191], v[58:61]
	s_barrier
	v_mfma_f32_16x16x32_bf16 v[46:49], v[140:143], v[196:199], v[46:49]
	v_mfma_f32_16x16x32_bf16 v[42:45], v[148:151], v[196:199], v[42:45]
	v_mfma_f32_16x16x32_bf16 v[30:33], v[140:143], v[204:207], v[30:33]
	v_mfma_f32_16x16x32_bf16 v[26:29], v[148:151], v[204:207], v[26:29]
	v_mfma_f32_16x16x32_bf16 v[14:17], v[140:143], v[222:225], v[14:17]
	v_mfma_f32_16x16x32_bf16 v[10:13], v[148:151], v[222:225], v[10:13]
	v_mfma_f32_16x16x32_bf16 v[62:65], v[144:147], v[192:195], v[62:65]
	v_mfma_f32_16x16x32_bf16 v[58:61], v[152:155], v[192:195], v[58:61]
	v_mfma_f32_16x16x32_bf16 v[46:49], v[144:147], v[200:203], v[46:49]
	v_mfma_f32_16x16x32_bf16 v[42:45], v[152:155], v[200:203], v[42:45]
	v_mfma_f32_16x16x32_bf16 v[30:33], v[144:147], v[218:221], v[30:33]
	v_mfma_f32_16x16x32_bf16 v[26:29], v[152:155], v[218:221], v[26:29]
	v_mfma_f32_16x16x32_bf16 v[14:17], v[144:147], v[226:229], v[14:17]
	v_mfma_f32_16x16x32_bf16 v[10:13], v[152:155], v[226:229], v[10:13]
	v_mfma_f32_16x16x32_bf16 v[54:57], v[156:159], v[188:191], v[54:57]
	v_mfma_f32_16x16x32_bf16 v[50:53], v[170:173], v[188:191], v[50:53]
	v_mfma_f32_16x16x32_bf16 v[38:41], v[156:159], v[196:199], v[38:41]
	v_mfma_f32_16x16x32_bf16 v[34:37], v[170:173], v[196:199], v[34:37]
	v_mfma_f32_16x16x32_bf16 v[22:25], v[156:159], v[204:207], v[22:25]
	v_mfma_f32_16x16x32_bf16 v[18:21], v[170:173], v[204:207], v[18:21]
	v_mfma_f32_16x16x32_bf16 v[6:9], v[156:159], v[222:225], v[6:9]
	v_mfma_f32_16x16x32_bf16 v[2:5], v[170:173], v[222:225], v[2:5]
	v_mfma_f32_16x16x32_bf16 v[54:57], v[166:169], v[192:195], v[54:57]
	v_mfma_f32_16x16x32_bf16 v[50:53], v[174:177], v[192:195], v[50:53]
	v_mfma_f32_16x16x32_bf16 v[38:41], v[166:169], v[200:203], v[38:41]
	v_mfma_f32_16x16x32_bf16 v[34:37], v[174:177], v[200:203], v[34:37]
	v_mfma_f32_16x16x32_bf16 v[22:25], v[166:169], v[218:221], v[22:25]
	v_mfma_f32_16x16x32_bf16 v[18:21], v[174:177], v[218:221], v[18:21]
	v_mfma_f32_16x16x32_bf16 v[6:9], v[166:169], v[226:229], v[6:9]
	v_mfma_f32_16x16x32_bf16 v[2:5], v[174:177], v[226:229], v[2:5]
	s_barrier
	s_add_i32 s3, 0, 0x18000
	s_add_i32 s42, 0, 0x1c000
	v_add_u32_e32 v152, s3, v163
	v_add_u32_e32 v174, s42, v163
	ds_read_b128 v[140:143], v152
	ds_read_b128 v[144:147], v152 offset:1024
	ds_read_b128 v[148:151], v152 offset:2048
	ds_read_b128 v[152:155], v152 offset:3072
	ds_read_b128 v[156:159], v174
	ds_read_b128 v[166:169], v174 offset:1024
	ds_read_b128 v[170:173], v174 offset:2048
	ds_read_b128 v[174:177], v174 offset:3072
	s_add_u32 s20, s20, 0x80000
	s_addc_u32 s21, s21, 0
	s_mov_b32 m0, s24
	v_lshl_add_u64 v[184:185], s[20:21], 0, v[134:135]
	ds_read_b128 v[188:191], v165 offset:32768
	ds_read_b128 v[192:195], v165 offset:33792
	ds_read_b128 v[196:199], v165 offset:34816
	ds_read_b128 v[200:203], v165 offset:35840
	ds_read_b128 v[204:207], v165 offset:36864
	ds_read_b128 v[218:221], v165 offset:37888
	ds_read_b128 v[222:225], v165 offset:38912
	ds_read_b128 v[226:229], v165 offset:39936
	global_load_lds_dwordx4 v[184:185], off
	v_lshl_add_u64 v[184:185], s[20:21], 0, v[132:133]
	s_mov_b32 m0, s25
	s_nop 0
	global_load_lds_dwordx4 v[184:185], off
	s_waitcnt vmcnt(8)
	s_waitcnt lgkmcnt(0)
	s_waitcnt lgkmcnt(0)
	v_mfma_f32_16x16x32_bf16 v[126:129], v[140:143], v[188:191], v[126:129]
	v_mfma_f32_16x16x32_bf16 v[122:125], v[148:151], v[188:191], v[122:125]
	s_barrier
	v_mfma_f32_16x16x32_bf16 v[110:113], v[140:143], v[196:199], v[110:113]
	v_mfma_f32_16x16x32_bf16 v[106:109], v[148:151], v[196:199], v[106:109]
	v_mfma_f32_16x16x32_bf16 v[94:97], v[140:143], v[204:207], v[94:97]
	v_mfma_f32_16x16x32_bf16 v[90:93], v[148:151], v[204:207], v[90:93]
	v_mfma_f32_16x16x32_bf16 v[78:81], v[140:143], v[222:225], v[78:81]
	v_mfma_f32_16x16x32_bf16 v[74:77], v[148:151], v[222:225], v[74:77]
	v_mfma_f32_16x16x32_bf16 v[126:129], v[144:147], v[192:195], v[126:129]
	v_mfma_f32_16x16x32_bf16 v[122:125], v[152:155], v[192:195], v[122:125]
	v_mfma_f32_16x16x32_bf16 v[110:113], v[144:147], v[200:203], v[110:113]
	v_mfma_f32_16x16x32_bf16 v[106:109], v[152:155], v[200:203], v[106:109]
	v_mfma_f32_16x16x32_bf16 v[94:97], v[144:147], v[218:221], v[94:97]
	v_mfma_f32_16x16x32_bf16 v[90:93], v[152:155], v[218:221], v[90:93]
	v_mfma_f32_16x16x32_bf16 v[78:81], v[144:147], v[226:229], v[78:81]
	v_mfma_f32_16x16x32_bf16 v[74:77], v[152:155], v[226:229], v[74:77]
	v_mfma_f32_16x16x32_bf16 v[118:121], v[156:159], v[188:191], v[118:121]
	v_mfma_f32_16x16x32_bf16 v[114:117], v[170:173], v[188:191], v[114:117]
	v_mfma_f32_16x16x32_bf16 v[102:105], v[156:159], v[196:199], v[102:105]
	v_mfma_f32_16x16x32_bf16 v[98:101], v[170:173], v[196:199], v[98:101]
	v_mfma_f32_16x16x32_bf16 v[86:89], v[156:159], v[204:207], v[86:89]
	v_mfma_f32_16x16x32_bf16 v[82:85], v[170:173], v[204:207], v[82:85]
	v_mfma_f32_16x16x32_bf16 v[70:73], v[156:159], v[222:225], v[70:73]
	v_mfma_f32_16x16x32_bf16 v[66:69], v[170:173], v[222:225], v[66:69]
	v_mfma_f32_16x16x32_bf16 v[118:121], v[166:169], v[192:195], v[118:121]
	v_mfma_f32_16x16x32_bf16 v[114:117], v[174:177], v[192:195], v[114:117]
	v_mfma_f32_16x16x32_bf16 v[102:105], v[166:169], v[200:203], v[102:105]
	v_mfma_f32_16x16x32_bf16 v[98:101], v[174:177], v[200:203], v[98:101]
	v_mfma_f32_16x16x32_bf16 v[86:89], v[166:169], v[218:221], v[86:89]
	v_mfma_f32_16x16x32_bf16 v[82:85], v[174:177], v[218:221], v[82:85]
	v_mfma_f32_16x16x32_bf16 v[70:73], v[166:169], v[226:229], v[70:73]
	v_mfma_f32_16x16x32_bf16 v[66:69], v[174:177], v[226:229], v[66:69]
	s_barrier
	s_add_i32 s3, s3, s2
	v_lshl_add_u64 v[160:161], v[160:161], 0, s[52:53]
	s_mov_b32 m0, s3
	ds_read_b128 v[188:191], v165 offset:49152
	ds_read_b128 v[192:195], v165 offset:50176
	ds_read_b128 v[196:199], v165 offset:51200
	ds_read_b128 v[200:203], v165 offset:52224
	ds_read_b128 v[204:207], v165 offset:53248
	ds_read_b128 v[218:221], v165 offset:54272
	ds_read_b128 v[222:225], v165 offset:55296
	ds_read_b128 v[226:229], v165 offset:56320
	global_load_lds_dwordx4 v[160:161], off
	s_add_i32 m0, s3, 0x2000
	s_add_u32 s18, s18, 0x80080
	v_lshl_add_u64 v[160:161], v[178:179], 0, s[52:53]
	s_addc_u32 s19, s19, 0
	s_add_i32 s3, s42, s2
	global_load_lds_dwordx4 v[160:161], off
	v_lshl_add_u64 v[160:161], s[18:19], 0, v[0:1]
	s_mov_b32 m0, s3
	s_nop 0
	global_load_lds_dwordx4 v[160:161], off
	v_lshl_add_u64 v[160:161], s[18:19], 0, v[130:131]
	s_add_i32 m0, s3, 0x2000
	s_nop 0
	global_load_lds_dwordx4 v[160:161], off
	v_lshl_add_u64 v[160:161], v[180:181], 0, s[52:53]
	s_mov_b32 m0, s26
	s_nop 0
	global_load_lds_dwordx4 v[160:161], off
	v_lshl_add_u64 v[160:161], v[182:183], 0, s[52:53]
	s_mov_b32 m0, s27
	s_nop 0
	global_load_lds_dwordx4 v[160:161], off
	s_waitcnt vmcnt(8)
	s_waitcnt lgkmcnt(0)
	s_waitcnt lgkmcnt(0)
	v_mfma_f32_16x16x32_bf16 v[62:65], v[140:143], v[188:191], v[62:65]
	v_mfma_f32_16x16x32_bf16 v[58:61], v[148:151], v[188:191], v[58:61]
	s_barrier
	v_mfma_f32_16x16x32_bf16 v[46:49], v[140:143], v[196:199], v[46:49]
	v_mfma_f32_16x16x32_bf16 v[42:45], v[148:151], v[196:199], v[42:45]
	v_mfma_f32_16x16x32_bf16 v[30:33], v[140:143], v[204:207], v[30:33]
	v_mfma_f32_16x16x32_bf16 v[26:29], v[148:151], v[204:207], v[26:29]
	v_mfma_f32_16x16x32_bf16 v[14:17], v[140:143], v[222:225], v[14:17]
	v_mfma_f32_16x16x32_bf16 v[10:13], v[148:151], v[222:225], v[10:13]
	v_mfma_f32_16x16x32_bf16 v[62:65], v[144:147], v[192:195], v[62:65]
	v_mfma_f32_16x16x32_bf16 v[58:61], v[152:155], v[192:195], v[58:61]
	v_mfma_f32_16x16x32_bf16 v[46:49], v[144:147], v[200:203], v[46:49]
	v_mfma_f32_16x16x32_bf16 v[42:45], v[152:155], v[200:203], v[42:45]
	v_mfma_f32_16x16x32_bf16 v[30:33], v[144:147], v[218:221], v[30:33]
	v_mfma_f32_16x16x32_bf16 v[26:29], v[152:155], v[218:221], v[26:29]
	v_mfma_f32_16x16x32_bf16 v[14:17], v[144:147], v[226:229], v[14:17]
	v_mfma_f32_16x16x32_bf16 v[10:13], v[152:155], v[226:229], v[10:13]
	v_mfma_f32_16x16x32_bf16 v[54:57], v[156:159], v[188:191], v[54:57]
	v_mfma_f32_16x16x32_bf16 v[50:53], v[170:173], v[188:191], v[50:53]
	v_mfma_f32_16x16x32_bf16 v[38:41], v[156:159], v[196:199], v[38:41]
	v_mfma_f32_16x16x32_bf16 v[34:37], v[170:173], v[196:199], v[34:37]
	v_mfma_f32_16x16x32_bf16 v[22:25], v[156:159], v[204:207], v[22:25]
	v_mfma_f32_16x16x32_bf16 v[18:21], v[170:173], v[204:207], v[18:21]
	v_mfma_f32_16x16x32_bf16 v[6:9], v[156:159], v[222:225], v[6:9]
	v_mfma_f32_16x16x32_bf16 v[2:5], v[170:173], v[222:225], v[2:5]
	v_mfma_f32_16x16x32_bf16 v[54:57], v[166:169], v[192:195], v[54:57]
	v_mfma_f32_16x16x32_bf16 v[50:53], v[174:177], v[192:195], v[50:53]
	v_mfma_f32_16x16x32_bf16 v[38:41], v[166:169], v[200:203], v[38:41]
	v_mfma_f32_16x16x32_bf16 v[34:37], v[174:177], v[200:203], v[34:37]
	v_mfma_f32_16x16x32_bf16 v[22:25], v[166:169], v[218:221], v[22:25]
	v_mfma_f32_16x16x32_bf16 v[18:21], v[174:177], v[218:221], v[18:21]
	v_mfma_f32_16x16x32_bf16 v[6:9], v[166:169], v[226:229], v[6:9]
	v_mfma_f32_16x16x32_bf16 v[2:5], v[174:177], v[226:229], v[2:5]
	s_barrier
	s_add_i32 s41, s41, 2
	s_add_u32 s0, s0, 0x100
	s_addc_u32 s1, s1, 0
	s_add_u32 s35, s35, 0x100
	s_addc_u32 s40, s40, 0
	s_cmp_gt_u32 s41, 29
	s_cbranch_scc0 .LBB0_846
	s_and_b64 vcc, exec, s[8:9]
	s_movk_i32 s40, 0x4000
	s_movk_i32 s41, 0x6000
	s_cbranch_vccz .LBB0_849
	s_barrier

.LBB0_959:
	s_add_u32 s3, s16, 0xfff80080
	s_addc_u32 s18, s17, -1
	s_add_i32 s42, 0, 0x10000
	s_cmp_eq_u32 s46, 28
	s_cselect_b32 s21, s11, s18
	s_cselect_b32 s20, s40, s3
	v_add_u32_e32 v140, s42, v143
	s_cselect_b32 s19, s9, s45
	s_cselect_b32 s18, s41, s44
	s_add_i32 s3, 0, 0x14000
	ds_read_b128 v[146:149], v140
	ds_read_b128 v[150:153], v140 offset:1024
	ds_read_b128 v[154:157], v140 offset:2048
	ds_read_b128 v[158:161], v140 offset:3072
	v_add_u32_e32 v140, s3, v143
	ds_read_b128 v[162:165], v140
	ds_read_b128 v[166:169], v140 offset:1024
	ds_read_b128 v[170:173], v140 offset:2048
	ds_read_b128 v[174:177], v140 offset:3072
	v_lshl_add_u64 v[140:141], s[16:17], 0, v[136:137]
	s_add_i32 m0, s25, 0xc000
	ds_read_b128 v[188:191], v145
	ds_read_b128 v[192:195], v145 offset:1024
	ds_read_b128 v[196:199], v145 offset:2048
	ds_read_b128 v[200:203], v145 offset:3072
	ds_read_b128 v[204:207], v145 offset:4096
	ds_read_b128 v[218:221], v145 offset:5120
	ds_read_b128 v[222:225], v145 offset:6144
	ds_read_b128 v[226:229], v145 offset:7168
	global_load_lds_dwordx4 v[140:141], off
	v_lshl_add_u64 v[140:141], s[16:17], 0, v[138:139]
	s_add_i32 m0, s25, 0xe000
	s_nop 0
	global_load_lds_dwordx4 v[140:141], off
	s_waitcnt vmcnt(8)
	s_waitcnt lgkmcnt(0)
	s_waitcnt lgkmcnt(0)
	v_mfma_f32_16x16x32_bf16 v[126:129], v[146:149], v[188:191], v[126:129]
	v_mfma_f32_16x16x32_bf16 v[122:125], v[154:157], v[188:191], v[122:125]
	s_barrier
	v_mfma_f32_16x16x32_bf16 v[110:113], v[146:149], v[196:199], v[110:113]
	v_mfma_f32_16x16x32_bf16 v[106:109], v[154:157], v[196:199], v[106:109]
	v_mfma_f32_16x16x32_bf16 v[94:97], v[146:149], v[204:207], v[94:97]
	v_mfma_f32_16x16x32_bf16 v[90:93], v[154:157], v[204:207], v[90:93]
	v_mfma_f32_16x16x32_bf16 v[78:81], v[146:149], v[222:225], v[78:81]
	v_mfma_f32_16x16x32_bf16 v[74:77], v[154:157], v[222:225], v[74:77]
	v_mfma_f32_16x16x32_bf16 v[126:129], v[150:153], v[192:195], v[126:129]
	v_mfma_f32_16x16x32_bf16 v[122:125], v[158:161], v[192:195], v[122:125]
	v_mfma_f32_16x16x32_bf16 v[110:113], v[150:153], v[200:203], v[110:113]
	v_mfma_f32_16x16x32_bf16 v[106:109], v[158:161], v[200:203], v[106:109]
	v_mfma_f32_16x16x32_bf16 v[94:97], v[150:153], v[218:221], v[94:97]
	v_mfma_f32_16x16x32_bf16 v[90:93], v[158:161], v[218:221], v[90:93]
	v_mfma_f32_16x16x32_bf16 v[78:81], v[150:153], v[226:229], v[78:81]
	v_mfma_f32_16x16x32_bf16 v[74:77], v[158:161], v[226:229], v[74:77]
	v_mfma_f32_16x16x32_bf16 v[118:121], v[162:165], v[188:191], v[118:121]
	v_mfma_f32_16x16x32_bf16 v[114:117], v[170:173], v[188:191], v[114:117]
	v_mfma_f32_16x16x32_bf16 v[102:105], v[162:165], v[196:199], v[102:105]
	v_mfma_f32_16x16x32_bf16 v[98:101], v[170:173], v[196:199], v[98:101]
	v_mfma_f32_16x16x32_bf16 v[86:89], v[162:165], v[204:207], v[86:89]
	v_mfma_f32_16x16x32_bf16 v[82:85], v[170:173], v[204:207], v[82:85]
	v_mfma_f32_16x16x32_bf16 v[70:73], v[162:165], v[222:225], v[70:73]
	v_mfma_f32_16x16x32_bf16 v[66:69], v[170:173], v[222:225], v[66:69]
	v_mfma_f32_16x16x32_bf16 v[118:121], v[166:169], v[192:195], v[118:121]
	v_mfma_f32_16x16x32_bf16 v[114:117], v[174:177], v[192:195], v[114:117]
	v_mfma_f32_16x16x32_bf16 v[102:105], v[166:169], v[200:203], v[102:105]
	v_mfma_f32_16x16x32_bf16 v[98:101], v[174:177], v[200:203], v[98:101]
	v_mfma_f32_16x16x32_bf16 v[86:89], v[166:169], v[218:221], v[86:89]
	v_mfma_f32_16x16x32_bf16 v[82:85], v[174:177], v[218:221], v[82:85]
	v_mfma_f32_16x16x32_bf16 v[70:73], v[166:169], v[226:229], v[70:73]
	v_mfma_f32_16x16x32_bf16 v[66:69], v[174:177], v[226:229], v[66:69]
	s_barrier
	s_add_i32 s42, s42, s24
	v_lshl_add_u64 v[140:141], s[18:19], 0, v[0:1]
	s_mov_b32 m0, s42
	ds_read_b128 v[188:191], v145 offset:16384
	ds_read_b128 v[192:195], v145 offset:17408
	ds_read_b128 v[196:199], v145 offset:18432
	ds_read_b128 v[200:203], v145 offset:19456
	ds_read_b128 v[204:207], v145 offset:20480
	ds_read_b128 v[218:221], v145 offset:21504
	ds_read_b128 v[222:225], v145 offset:22528
	ds_read_b128 v[226:229], v145 offset:23552
	global_load_lds_dwordx4 v[140:141], off
	s_add_i32 m0, s42, 0x2000
	s_add_u32 s56, s18, 0x80000
	v_lshl_add_u64 v[178:179], s[18:19], 0, v[130:131]
	s_addc_u32 s57, s19, 0
	s_add_i32 s3, s3, s24
	global_load_lds_dwordx4 v[178:179], off
	v_lshl_add_u64 v[180:181], s[56:57], 0, v[0:1]
	s_mov_b32 m0, s3
	v_lshl_add_u64 v[182:183], s[20:21], 0, v[132:133]
	global_load_lds_dwordx4 v[180:181], off
	v_lshl_add_u64 v[180:181], s[56:57], 0, v[130:131]
	s_add_i32 m0, s3, 0x2000
	s_nop 0
	global_load_lds_dwordx4 v[180:181], off
	v_lshl_add_u64 v[180:181], s[20:21], 0, v[134:135]
	s_mov_b32 m0, s25
	s_nop 0
	global_load_lds_dwordx4 v[180:181], off
	s_mov_b32 m0, s26
	s_nop 0
	global_load_lds_dwordx4 v[182:183], off
	s_waitcnt vmcnt(8)
	s_waitcnt lgkmcnt(0)
	s_waitcnt lgkmcnt(0)
	v_mfma_f32_16x16x32_bf16 v[62:65], v[146:149], v[188:191], v[62:65]
	v_mfma_f32_16x16x32_bf16 v[58:61], v[154:157], v[188:191], v[58:61]
	s_barrier
	v_mfma_f32_16x16x32_bf16 v[46:49], v[146:149], v[196:199], v[46:49]
	v_mfma_f32_16x16x32_bf16 v[42:45], v[154:157], v[196:199], v[42:45]
	v_mfma_f32_16x16x32_bf16 v[30:33], v[146:149], v[204:207], v[30:33]
	v_mfma_f32_16x16x32_bf16 v[26:29], v[154:157], v[204:207], v[26:29]
	v_mfma_f32_16x16x32_bf16 v[14:17], v[146:149], v[222:225], v[14:17]
	v_mfma_f32_16x16x32_bf16 v[10:13], v[154:157], v[222:225], v[10:13]
	v_mfma_f32_16x16x32_bf16 v[62:65], v[150:153], v[192:195], v[62:65]
	v_mfma_f32_16x16x32_bf16 v[58:61], v[158:161], v[192:195], v[58:61]
	v_mfma_f32_16x16x32_bf16 v[46:49], v[150:153], v[200:203], v[46:49]
	v_mfma_f32_16x16x32_bf16 v[42:45], v[158:161], v[200:203], v[42:45]
	v_mfma_f32_16x16x32_bf16 v[30:33], v[150:153], v[218:221], v[30:33]
	v_mfma_f32_16x16x32_bf16 v[26:29], v[158:161], v[218:221], v[26:29]
	v_mfma_f32_16x16x32_bf16 v[14:17], v[150:153], v[226:229], v[14:17]
	v_mfma_f32_16x16x32_bf16 v[10:13], v[158:161], v[226:229], v[10:13]
	v_mfma_f32_16x16x32_bf16 v[54:57], v[162:165], v[188:191], v[54:57]
	v_mfma_f32_16x16x32_bf16 v[50:53], v[170:173], v[188:191], v[50:53]
	v_mfma_f32_16x16x32_bf16 v[38:41], v[162:165], v[196:199], v[38:41]
	v_mfma_f32_16x16x32_bf16 v[34:37], v[170:173], v[196:199], v[34:37]
	v_mfma_f32_16x16x32_bf16 v[22:25], v[162:165], v[204:207], v[22:25]
	v_mfma_f32_16x16x32_bf16 v[18:21], v[170:173], v[204:207], v[18:21]
	v_mfma_f32_16x16x32_bf16 v[6:9], v[162:165], v[222:225], v[6:9]
	v_mfma_f32_16x16x32_bf16 v[2:5], v[170:173], v[222:225], v[2:5]
	v_mfma_f32_16x16x32_bf16 v[54:57], v[166:169], v[192:195], v[54:57]
	v_mfma_f32_16x16x32_bf16 v[50:53], v[174:177], v[192:195], v[50:53]
	v_mfma_f32_16x16x32_bf16 v[38:41], v[166:169], v[200:203], v[38:41]
	v_mfma_f32_16x16x32_bf16 v[34:37], v[174:177], v[200:203], v[34:37]
	v_mfma_f32_16x16x32_bf16 v[22:25], v[166:169], v[218:221], v[22:25]
	v_mfma_f32_16x16x32_bf16 v[18:21], v[174:177], v[218:221], v[18:21]
	v_mfma_f32_16x16x32_bf16 v[6:9], v[166:169], v[226:229], v[6:9]
	v_mfma_f32_16x16x32_bf16 v[2:5], v[174:177], v[226:229], v[2:5]
	s_barrier
	s_add_i32 s3, 0, 0x18000
	s_add_i32 s42, 0, 0x1c000
	v_add_u32_e32 v158, s3, v143
	v_add_u32_e32 v174, s42, v143
	ds_read_b128 v[146:149], v158
	ds_read_b128 v[150:153], v158 offset:1024
	ds_read_b128 v[154:157], v158 offset:2048
	ds_read_b128 v[158:161], v158 offset:3072
	ds_read_b128 v[162:165], v174
	ds_read_b128 v[166:169], v174 offset:1024
	ds_read_b128 v[170:173], v174 offset:2048
	ds_read_b128 v[174:177], v174 offset:3072
	s_add_u32 s20, s20, 0x80000
	s_addc_u32 s21, s21, 0
	s_mov_b32 m0, s27
	v_lshl_add_u64 v[184:185], s[20:21], 0, v[134:135]
	ds_read_b128 v[188:191], v145 offset:32768
	ds_read_b128 v[192:195], v145 offset:33792
	ds_read_b128 v[196:199], v145 offset:34816
	ds_read_b128 v[200:203], v145 offset:35840
	ds_read_b128 v[204:207], v145 offset:36864
	ds_read_b128 v[218:221], v145 offset:37888
	ds_read_b128 v[222:225], v145 offset:38912
	ds_read_b128 v[226:229], v145 offset:39936
	global_load_lds_dwordx4 v[184:185], off
	v_lshl_add_u64 v[184:185], s[20:21], 0, v[132:133]
	s_mov_b32 m0, s28
	s_nop 0
	global_load_lds_dwordx4 v[184:185], off
	s_waitcnt vmcnt(8)
	s_waitcnt lgkmcnt(0)
	s_waitcnt lgkmcnt(0)
	v_mfma_f32_16x16x32_bf16 v[126:129], v[146:149], v[188:191], v[126:129]
	v_mfma_f32_16x16x32_bf16 v[122:125], v[154:157], v[188:191], v[122:125]
	s_barrier
	v_mfma_f32_16x16x32_bf16 v[110:113], v[146:149], v[196:199], v[110:113]
	v_mfma_f32_16x16x32_bf16 v[106:109], v[154:157], v[196:199], v[106:109]
	v_mfma_f32_16x16x32_bf16 v[94:97], v[146:149], v[204:207], v[94:97]
	v_mfma_f32_16x16x32_bf16 v[90:93], v[154:157], v[204:207], v[90:93]
	v_mfma_f32_16x16x32_bf16 v[78:81], v[146:149], v[222:225], v[78:81]
	v_mfma_f32_16x16x32_bf16 v[74:77], v[154:157], v[222:225], v[74:77]
	v_mfma_f32_16x16x32_bf16 v[126:129], v[150:153], v[192:195], v[126:129]
	v_mfma_f32_16x16x32_bf16 v[122:125], v[158:161], v[192:195], v[122:125]
	v_mfma_f32_16x16x32_bf16 v[110:113], v[150:153], v[200:203], v[110:113]
	v_mfma_f32_16x16x32_bf16 v[106:109], v[158:161], v[200:203], v[106:109]
	v_mfma_f32_16x16x32_bf16 v[94:97], v[150:153], v[218:221], v[94:97]
	v_mfma_f32_16x16x32_bf16 v[90:93], v[158:161], v[218:221], v[90:93]
	v_mfma_f32_16x16x32_bf16 v[78:81], v[150:153], v[226:229], v[78:81]
	v_mfma_f32_16x16x32_bf16 v[74:77], v[158:161], v[226:229], v[74:77]
	v_mfma_f32_16x16x32_bf16 v[118:121], v[162:165], v[188:191], v[118:121]
	v_mfma_f32_16x16x32_bf16 v[114:117], v[170:173], v[188:191], v[114:117]
	v_mfma_f32_16x16x32_bf16 v[102:105], v[162:165], v[196:199], v[102:105]
	v_mfma_f32_16x16x32_bf16 v[98:101], v[170:173], v[196:199], v[98:101]
	v_mfma_f32_16x16x32_bf16 v[86:89], v[162:165], v[204:207], v[86:89]
	v_mfma_f32_16x16x32_bf16 v[82:85], v[170:173], v[204:207], v[82:85]
	v_mfma_f32_16x16x32_bf16 v[70:73], v[162:165], v[222:225], v[70:73]
	v_mfma_f32_16x16x32_bf16 v[66:69], v[170:173], v[222:225], v[66:69]
	v_mfma_f32_16x16x32_bf16 v[118:121], v[166:169], v[192:195], v[118:121]
	v_mfma_f32_16x16x32_bf16 v[114:117], v[174:177], v[192:195], v[114:117]
	v_mfma_f32_16x16x32_bf16 v[102:105], v[166:169], v[200:203], v[102:105]
	v_mfma_f32_16x16x32_bf16 v[98:101], v[174:177], v[200:203], v[98:101]
	v_mfma_f32_16x16x32_bf16 v[86:89], v[166:169], v[218:221], v[86:89]
	v_mfma_f32_16x16x32_bf16 v[82:85], v[174:177], v[218:221], v[82:85]
	v_mfma_f32_16x16x32_bf16 v[70:73], v[166:169], v[226:229], v[70:73]
	v_mfma_f32_16x16x32_bf16 v[66:69], v[174:177], v[226:229], v[66:69]
	s_barrier
	s_add_i32 s3, s3, s24
	v_lshl_add_u64 v[140:141], v[140:141], 0, s[52:53]
	s_mov_b32 m0, s3
	ds_read_b128 v[188:191], v145 offset:49152
	ds_read_b128 v[192:195], v145 offset:50176
	ds_read_b128 v[196:199], v145 offset:51200
	ds_read_b128 v[200:203], v145 offset:52224
	ds_read_b128 v[204:207], v145 offset:53248
	ds_read_b128 v[218:221], v145 offset:54272
	ds_read_b128 v[222:225], v145 offset:55296
	ds_read_b128 v[226:229], v145 offset:56320
	global_load_lds_dwordx4 v[140:141], off
	s_add_i32 m0, s3, 0x2000
	s_add_u32 s18, s18, 0x80080
	v_lshl_add_u64 v[140:141], v[178:179], 0, s[52:53]
	s_addc_u32 s19, s19, 0
	s_add_i32 s3, s42, s24
	global_load_lds_dwordx4 v[140:141], off
	v_lshl_add_u64 v[140:141], s[18:19], 0, v[0:1]
	s_mov_b32 m0, s3
	s_nop 0
	global_load_lds_dwordx4 v[140:141], off
	v_lshl_add_u64 v[140:141], s[18:19], 0, v[130:131]
	s_add_i32 m0, s3, 0x2000
	s_nop 0
	global_load_lds_dwordx4 v[140:141], off
	v_lshl_add_u64 v[140:141], v[180:181], 0, s[52:53]
	s_mov_b32 m0, s29
	s_nop 0
	global_load_lds_dwordx4 v[140:141], off
	v_lshl_add_u64 v[140:141], v[182:183], 0, s[52:53]
	s_mov_b32 m0, s30
	s_nop 0
	global_load_lds_dwordx4 v[140:141], off
	s_waitcnt vmcnt(8)
	s_waitcnt lgkmcnt(0)
	s_waitcnt lgkmcnt(0)
	v_mfma_f32_16x16x32_bf16 v[62:65], v[146:149], v[188:191], v[62:65]
	v_mfma_f32_16x16x32_bf16 v[58:61], v[154:157], v[188:191], v[58:61]
	s_barrier
	v_mfma_f32_16x16x32_bf16 v[46:49], v[146:149], v[196:199], v[46:49]
	v_mfma_f32_16x16x32_bf16 v[42:45], v[154:157], v[196:199], v[42:45]
	v_mfma_f32_16x16x32_bf16 v[30:33], v[146:149], v[204:207], v[30:33]
	v_mfma_f32_16x16x32_bf16 v[26:29], v[154:157], v[204:207], v[26:29]
	v_mfma_f32_16x16x32_bf16 v[14:17], v[146:149], v[222:225], v[14:17]
	v_mfma_f32_16x16x32_bf16 v[10:13], v[154:157], v[222:225], v[10:13]
	v_mfma_f32_16x16x32_bf16 v[62:65], v[150:153], v[192:195], v[62:65]
	v_mfma_f32_16x16x32_bf16 v[58:61], v[158:161], v[192:195], v[58:61]
	v_mfma_f32_16x16x32_bf16 v[46:49], v[150:153], v[200:203], v[46:49]
	v_mfma_f32_16x16x32_bf16 v[42:45], v[158:161], v[200:203], v[42:45]
	v_mfma_f32_16x16x32_bf16 v[30:33], v[150:153], v[218:221], v[30:33]
	v_mfma_f32_16x16x32_bf16 v[26:29], v[158:161], v[218:221], v[26:29]
	v_mfma_f32_16x16x32_bf16 v[14:17], v[150:153], v[226:229], v[14:17]
	v_mfma_f32_16x16x32_bf16 v[10:13], v[158:161], v[226:229], v[10:13]
	v_mfma_f32_16x16x32_bf16 v[54:57], v[162:165], v[188:191], v[54:57]
	v_mfma_f32_16x16x32_bf16 v[50:53], v[170:173], v[188:191], v[50:53]
	v_mfma_f32_16x16x32_bf16 v[38:41], v[162:165], v[196:199], v[38:41]
	v_mfma_f32_16x16x32_bf16 v[34:37], v[170:173], v[196:199], v[34:37]
	v_mfma_f32_16x16x32_bf16 v[22:25], v[162:165], v[204:207], v[22:25]
	v_mfma_f32_16x16x32_bf16 v[18:21], v[170:173], v[204:207], v[18:21]
	v_mfma_f32_16x16x32_bf16 v[6:9], v[162:165], v[222:225], v[6:9]
	v_mfma_f32_16x16x32_bf16 v[2:5], v[170:173], v[222:225], v[2:5]
	v_mfma_f32_16x16x32_bf16 v[54:57], v[166:169], v[192:195], v[54:57]
	v_mfma_f32_16x16x32_bf16 v[50:53], v[174:177], v[192:195], v[50:53]
	v_mfma_f32_16x16x32_bf16 v[38:41], v[166:169], v[200:203], v[38:41]
	v_mfma_f32_16x16x32_bf16 v[34:37], v[174:177], v[200:203], v[34:37]
	v_mfma_f32_16x16x32_bf16 v[22:25], v[166:169], v[218:221], v[22:25]
	v_mfma_f32_16x16x32_bf16 v[18:21], v[174:177], v[218:221], v[18:21]
	v_mfma_f32_16x16x32_bf16 v[6:9], v[166:169], v[226:229], v[6:9]
	v_mfma_f32_16x16x32_bf16 v[2:5], v[174:177], v[226:229], v[2:5]
	s_barrier
	s_add_i32 s46, s46, 2
	s_add_u32 s16, s16, 0x100
	s_addc_u32 s17, s17, 0
	s_add_u32 s44, s44, 0x100
	s_addc_u32 s45, s45, 0
	s_cmp_gt_u32 s46, 29
	s_cbranch_scc0 .LBB0_959
	s_and_b64 vcc, exec, s[6:7]
	s_movk_i32 s40, 0x4000
	s_movk_i32 s41, 0x6000
	s_mov_b32 s44, 0x8000
	s_mov_b32 s45, 0xa000
	s_cbranch_vccz .LBB0_962
	s_barrier

.LBB0_1024:
	s_add_u32 s3, s20, 0xffe00080
	s_addc_u32 s22, s21, -1
	s_add_i32 s42, 0, 0x10000
	s_cmpk_eq_i32 s57, 0x7c
	s_cselect_b32 s25, s15, s22
	s_cselect_b32 s24, s45, s3
	s_cselect_b32 s23, s13, s56
	s_cselect_b32 s22, s46, s47
	s_add_i32 s3, 0, 0x14000
	v_add_u32_e32 v152, s42, v163
	v_add_u32_e32 v160, s3, v163
	ds_read_b128 v[140:143], v152
	ds_read_b128 v[144:147], v152 offset:1024
	ds_read_b128 v[148:151], v152 offset:2048
	ds_read_b128 v[152:155], v152 offset:3072
	ds_read_b128 v[156:159], v160
	ds_read_b128 v[166:169], v160 offset:1024
	ds_read_b128 v[170:173], v160 offset:2048
	ds_read_b128 v[174:177], v160 offset:3072
	v_lshl_add_u64 v[160:161], s[20:21], 0, v[136:137]
	s_add_i32 m0, s28, 0xc000
	ds_read_b128 v[188:191], v165
	ds_read_b128 v[192:195], v165 offset:1024
	ds_read_b128 v[196:199], v165 offset:2048
	ds_read_b128 v[200:203], v165 offset:3072
	ds_read_b128 v[204:207], v165 offset:4096
	ds_read_b128 v[218:221], v165 offset:5120
	ds_read_b128 v[222:225], v165 offset:6144
	ds_read_b128 v[226:229], v165 offset:7168
	global_load_lds_dwordx4 v[160:161], off
	v_lshl_add_u64 v[160:161], s[20:21], 0, v[138:139]
	s_add_i32 m0, s28, 0xe000
	s_nop 0
	global_load_lds_dwordx4 v[160:161], off
	s_waitcnt vmcnt(8)
	s_waitcnt lgkmcnt(0)
	s_waitcnt lgkmcnt(0)
	v_mfma_f32_16x16x32_bf16 v[126:129], v[140:143], v[188:191], v[126:129]
	v_mfma_f32_16x16x32_bf16 v[122:125], v[148:151], v[188:191], v[122:125]
	s_barrier
	v_mfma_f32_16x16x32_bf16 v[110:113], v[140:143], v[196:199], v[110:113]
	v_mfma_f32_16x16x32_bf16 v[106:109], v[148:151], v[196:199], v[106:109]
	v_mfma_f32_16x16x32_bf16 v[94:97], v[140:143], v[204:207], v[94:97]
	v_mfma_f32_16x16x32_bf16 v[90:93], v[148:151], v[204:207], v[90:93]
	v_mfma_f32_16x16x32_bf16 v[78:81], v[140:143], v[222:225], v[78:81]
	v_mfma_f32_16x16x32_bf16 v[74:77], v[148:151], v[222:225], v[74:77]
	v_mfma_f32_16x16x32_bf16 v[126:129], v[144:147], v[192:195], v[126:129]
	v_mfma_f32_16x16x32_bf16 v[122:125], v[152:155], v[192:195], v[122:125]
	v_mfma_f32_16x16x32_bf16 v[110:113], v[144:147], v[200:203], v[110:113]
	v_mfma_f32_16x16x32_bf16 v[106:109], v[152:155], v[200:203], v[106:109]
	v_mfma_f32_16x16x32_bf16 v[94:97], v[144:147], v[218:221], v[94:97]
	v_mfma_f32_16x16x32_bf16 v[90:93], v[152:155], v[218:221], v[90:93]
	v_mfma_f32_16x16x32_bf16 v[78:81], v[144:147], v[226:229], v[78:81]
	v_mfma_f32_16x16x32_bf16 v[74:77], v[152:155], v[226:229], v[74:77]
	v_mfma_f32_16x16x32_bf16 v[118:121], v[156:159], v[188:191], v[118:121]
	v_mfma_f32_16x16x32_bf16 v[114:117], v[170:173], v[188:191], v[114:117]
	v_mfma_f32_16x16x32_bf16 v[102:105], v[156:159], v[196:199], v[102:105]
	v_mfma_f32_16x16x32_bf16 v[98:101], v[170:173], v[196:199], v[98:101]
	v_mfma_f32_16x16x32_bf16 v[86:89], v[156:159], v[204:207], v[86:89]
	v_mfma_f32_16x16x32_bf16 v[82:85], v[170:173], v[204:207], v[82:85]
	v_mfma_f32_16x16x32_bf16 v[70:73], v[156:159], v[222:225], v[70:73]
	v_mfma_f32_16x16x32_bf16 v[66:69], v[170:173], v[222:225], v[66:69]
	v_mfma_f32_16x16x32_bf16 v[118:121], v[166:169], v[192:195], v[118:121]
	v_mfma_f32_16x16x32_bf16 v[114:117], v[174:177], v[192:195], v[114:117]
	v_mfma_f32_16x16x32_bf16 v[102:105], v[166:169], v[200:203], v[102:105]
	v_mfma_f32_16x16x32_bf16 v[98:101], v[174:177], v[200:203], v[98:101]
	v_mfma_f32_16x16x32_bf16 v[86:89], v[166:169], v[218:221], v[86:89]
	v_mfma_f32_16x16x32_bf16 v[82:85], v[174:177], v[218:221], v[82:85]
	v_mfma_f32_16x16x32_bf16 v[70:73], v[166:169], v[226:229], v[70:73]
	v_mfma_f32_16x16x32_bf16 v[66:69], v[174:177], v[226:229], v[66:69]
	s_barrier
	s_add_i32 s42, s42, s27
	v_lshl_add_u64 v[160:161], s[22:23], 0, v[0:1]
	s_mov_b32 m0, s42
	ds_read_b128 v[188:191], v165 offset:16384
	ds_read_b128 v[192:195], v165 offset:17408
	ds_read_b128 v[196:199], v165 offset:18432
	ds_read_b128 v[200:203], v165 offset:19456
	ds_read_b128 v[204:207], v165 offset:20480
	ds_read_b128 v[218:221], v165 offset:21504
	ds_read_b128 v[222:225], v165 offset:22528
	ds_read_b128 v[226:229], v165 offset:23552
	global_load_lds_dwordx4 v[160:161], off
	s_add_i32 m0, s42, 0x2000
	s_add_u32 s58, s22, 0x200000
	v_lshl_add_u64 v[178:179], s[22:23], 0, v[130:131]
	s_addc_u32 s59, s23, 0
	s_add_i32 s3, s3, s27
	global_load_lds_dwordx4 v[178:179], off
	v_lshl_add_u64 v[180:181], s[58:59], 0, v[0:1]
	s_mov_b32 m0, s3
	v_lshl_add_u64 v[182:183], s[24:25], 0, v[132:133]
	global_load_lds_dwordx4 v[180:181], off
	v_lshl_add_u64 v[180:181], s[58:59], 0, v[130:131]
	s_add_i32 m0, s3, 0x2000
	s_nop 0
	global_load_lds_dwordx4 v[180:181], off
	v_lshl_add_u64 v[180:181], s[24:25], 0, v[134:135]
	s_mov_b32 m0, s28
	s_nop 0
	global_load_lds_dwordx4 v[180:181], off
	s_mov_b32 m0, s29
	s_nop 0
	global_load_lds_dwordx4 v[182:183], off
	s_waitcnt vmcnt(8)
	s_waitcnt lgkmcnt(0)
	s_waitcnt lgkmcnt(0)
	v_mfma_f32_16x16x32_bf16 v[62:65], v[140:143], v[188:191], v[62:65]
	v_mfma_f32_16x16x32_bf16 v[58:61], v[148:151], v[188:191], v[58:61]
	s_barrier
	v_mfma_f32_16x16x32_bf16 v[46:49], v[140:143], v[196:199], v[46:49]
	v_mfma_f32_16x16x32_bf16 v[42:45], v[148:151], v[196:199], v[42:45]
	v_mfma_f32_16x16x32_bf16 v[30:33], v[140:143], v[204:207], v[30:33]
	v_mfma_f32_16x16x32_bf16 v[26:29], v[148:151], v[204:207], v[26:29]
	v_mfma_f32_16x16x32_bf16 v[14:17], v[140:143], v[222:225], v[14:17]
	v_mfma_f32_16x16x32_bf16 v[10:13], v[148:151], v[222:225], v[10:13]
	v_mfma_f32_16x16x32_bf16 v[62:65], v[144:147], v[192:195], v[62:65]
	v_mfma_f32_16x16x32_bf16 v[58:61], v[152:155], v[192:195], v[58:61]
	v_mfma_f32_16x16x32_bf16 v[46:49], v[144:147], v[200:203], v[46:49]
	v_mfma_f32_16x16x32_bf16 v[42:45], v[152:155], v[200:203], v[42:45]
	v_mfma_f32_16x16x32_bf16 v[30:33], v[144:147], v[218:221], v[30:33]
	v_mfma_f32_16x16x32_bf16 v[26:29], v[152:155], v[218:221], v[26:29]
	v_mfma_f32_16x16x32_bf16 v[14:17], v[144:147], v[226:229], v[14:17]
	v_mfma_f32_16x16x32_bf16 v[10:13], v[152:155], v[226:229], v[10:13]
	v_mfma_f32_16x16x32_bf16 v[54:57], v[156:159], v[188:191], v[54:57]
	v_mfma_f32_16x16x32_bf16 v[50:53], v[170:173], v[188:191], v[50:53]
	v_mfma_f32_16x16x32_bf16 v[38:41], v[156:159], v[196:199], v[38:41]
	v_mfma_f32_16x16x32_bf16 v[34:37], v[170:173], v[196:199], v[34:37]
	v_mfma_f32_16x16x32_bf16 v[22:25], v[156:159], v[204:207], v[22:25]
	v_mfma_f32_16x16x32_bf16 v[18:21], v[170:173], v[204:207], v[18:21]
	v_mfma_f32_16x16x32_bf16 v[6:9], v[156:159], v[222:225], v[6:9]
	v_mfma_f32_16x16x32_bf16 v[2:5], v[170:173], v[222:225], v[2:5]
	v_mfma_f32_16x16x32_bf16 v[54:57], v[166:169], v[192:195], v[54:57]
	v_mfma_f32_16x16x32_bf16 v[50:53], v[174:177], v[192:195], v[50:53]
	v_mfma_f32_16x16x32_bf16 v[38:41], v[166:169], v[200:203], v[38:41]
	v_mfma_f32_16x16x32_bf16 v[34:37], v[174:177], v[200:203], v[34:37]
	v_mfma_f32_16x16x32_bf16 v[22:25], v[166:169], v[218:221], v[22:25]
	v_mfma_f32_16x16x32_bf16 v[18:21], v[174:177], v[218:221], v[18:21]
	v_mfma_f32_16x16x32_bf16 v[6:9], v[166:169], v[226:229], v[6:9]
	v_mfma_f32_16x16x32_bf16 v[2:5], v[174:177], v[226:229], v[2:5]
	s_barrier
	s_add_i32 s3, 0, 0x18000
	s_add_i32 s42, 0, 0x1c000
	v_add_u32_e32 v152, s3, v163
	v_add_u32_e32 v174, s42, v163
	ds_read_b128 v[140:143], v152
	ds_read_b128 v[144:147], v152 offset:1024
	ds_read_b128 v[148:151], v152 offset:2048
	ds_read_b128 v[152:155], v152 offset:3072
	ds_read_b128 v[156:159], v174
	ds_read_b128 v[166:169], v174 offset:1024
	ds_read_b128 v[170:173], v174 offset:2048
	ds_read_b128 v[174:177], v174 offset:3072
	s_add_u32 s24, s24, 0x200000
	s_addc_u32 s25, s25, 0
	s_mov_b32 m0, s30
	v_lshl_add_u64 v[184:185], s[24:25], 0, v[134:135]
	ds_read_b128 v[188:191], v165 offset:32768
	ds_read_b128 v[192:195], v165 offset:33792
	ds_read_b128 v[196:199], v165 offset:34816
	ds_read_b128 v[200:203], v165 offset:35840
	ds_read_b128 v[204:207], v165 offset:36864
	ds_read_b128 v[218:221], v165 offset:37888
	ds_read_b128 v[222:225], v165 offset:38912
	ds_read_b128 v[226:229], v165 offset:39936
	global_load_lds_dwordx4 v[184:185], off
	v_lshl_add_u64 v[184:185], s[24:25], 0, v[132:133]
	s_mov_b32 m0, s31
	s_nop 0
	global_load_lds_dwordx4 v[184:185], off
	s_waitcnt vmcnt(8)
	s_waitcnt lgkmcnt(0)
	s_waitcnt lgkmcnt(0)
	v_mfma_f32_16x16x32_bf16 v[126:129], v[140:143], v[188:191], v[126:129]
	v_mfma_f32_16x16x32_bf16 v[122:125], v[148:151], v[188:191], v[122:125]
	s_barrier
	v_mfma_f32_16x16x32_bf16 v[110:113], v[140:143], v[196:199], v[110:113]
	v_mfma_f32_16x16x32_bf16 v[106:109], v[148:151], v[196:199], v[106:109]
	v_mfma_f32_16x16x32_bf16 v[94:97], v[140:143], v[204:207], v[94:97]
	v_mfma_f32_16x16x32_bf16 v[90:93], v[148:151], v[204:207], v[90:93]
	v_mfma_f32_16x16x32_bf16 v[78:81], v[140:143], v[222:225], v[78:81]
	v_mfma_f32_16x16x32_bf16 v[74:77], v[148:151], v[222:225], v[74:77]
	v_mfma_f32_16x16x32_bf16 v[126:129], v[144:147], v[192:195], v[126:129]
	v_mfma_f32_16x16x32_bf16 v[122:125], v[152:155], v[192:195], v[122:125]
	v_mfma_f32_16x16x32_bf16 v[110:113], v[144:147], v[200:203], v[110:113]
	v_mfma_f32_16x16x32_bf16 v[106:109], v[152:155], v[200:203], v[106:109]
	v_mfma_f32_16x16x32_bf16 v[94:97], v[144:147], v[218:221], v[94:97]
	v_mfma_f32_16x16x32_bf16 v[90:93], v[152:155], v[218:221], v[90:93]
	v_mfma_f32_16x16x32_bf16 v[78:81], v[144:147], v[226:229], v[78:81]
	v_mfma_f32_16x16x32_bf16 v[74:77], v[152:155], v[226:229], v[74:77]
	v_mfma_f32_16x16x32_bf16 v[118:121], v[156:159], v[188:191], v[118:121]
	v_mfma_f32_16x16x32_bf16 v[114:117], v[170:173], v[188:191], v[114:117]
	v_mfma_f32_16x16x32_bf16 v[102:105], v[156:159], v[196:199], v[102:105]
	v_mfma_f32_16x16x32_bf16 v[98:101], v[170:173], v[196:199], v[98:101]
	v_mfma_f32_16x16x32_bf16 v[86:89], v[156:159], v[204:207], v[86:89]
	v_mfma_f32_16x16x32_bf16 v[82:85], v[170:173], v[204:207], v[82:85]
	v_mfma_f32_16x16x32_bf16 v[70:73], v[156:159], v[222:225], v[70:73]
	v_mfma_f32_16x16x32_bf16 v[66:69], v[170:173], v[222:225], v[66:69]
	v_mfma_f32_16x16x32_bf16 v[118:121], v[166:169], v[192:195], v[118:121]
	v_mfma_f32_16x16x32_bf16 v[114:117], v[174:177], v[192:195], v[114:117]
	v_mfma_f32_16x16x32_bf16 v[102:105], v[166:169], v[200:203], v[102:105]
	v_mfma_f32_16x16x32_bf16 v[98:101], v[174:177], v[200:203], v[98:101]
	v_mfma_f32_16x16x32_bf16 v[86:89], v[166:169], v[218:221], v[86:89]
	v_mfma_f32_16x16x32_bf16 v[82:85], v[174:177], v[218:221], v[82:85]
	v_mfma_f32_16x16x32_bf16 v[70:73], v[166:169], v[226:229], v[70:73]
	v_mfma_f32_16x16x32_bf16 v[66:69], v[174:177], v[226:229], v[66:69]
	s_barrier
	s_add_i32 s3, s3, s27
	v_lshl_add_u64 v[160:161], v[160:161], 0, s[52:53]
	s_mov_b32 m0, s3
	ds_read_b128 v[188:191], v165 offset:49152
	ds_read_b128 v[192:195], v165 offset:50176
	ds_read_b128 v[196:199], v165 offset:51200
	ds_read_b128 v[200:203], v165 offset:52224
	ds_read_b128 v[204:207], v165 offset:53248
	ds_read_b128 v[218:221], v165 offset:54272
	ds_read_b128 v[222:225], v165 offset:55296
	ds_read_b128 v[226:229], v165 offset:56320
	global_load_lds_dwordx4 v[160:161], off
	s_add_i32 m0, s3, 0x2000
	s_add_u32 s22, s22, 0x200080
	v_lshl_add_u64 v[160:161], v[178:179], 0, s[52:53]
	s_addc_u32 s23, s23, 0
	s_add_i32 s3, s42, s27
	global_load_lds_dwordx4 v[160:161], off
	v_lshl_add_u64 v[160:161], s[22:23], 0, v[0:1]
	s_mov_b32 m0, s3
	s_nop 0
	global_load_lds_dwordx4 v[160:161], off
	v_lshl_add_u64 v[160:161], s[22:23], 0, v[130:131]
	s_add_i32 m0, s3, 0x2000
	s_nop 0
	global_load_lds_dwordx4 v[160:161], off
	v_lshl_add_u64 v[160:161], v[180:181], 0, s[52:53]
	s_mov_b32 m0, s34
	s_nop 0
	global_load_lds_dwordx4 v[160:161], off
	v_lshl_add_u64 v[160:161], v[182:183], 0, s[52:53]
	s_mov_b32 m0, s35
	s_nop 0
	global_load_lds_dwordx4 v[160:161], off
	s_waitcnt vmcnt(8)
	s_waitcnt lgkmcnt(0)
	s_waitcnt lgkmcnt(0)
	v_mfma_f32_16x16x32_bf16 v[62:65], v[140:143], v[188:191], v[62:65]
	v_mfma_f32_16x16x32_bf16 v[58:61], v[148:151], v[188:191], v[58:61]
	s_barrier
	v_mfma_f32_16x16x32_bf16 v[46:49], v[140:143], v[196:199], v[46:49]
	v_mfma_f32_16x16x32_bf16 v[42:45], v[148:151], v[196:199], v[42:45]
	v_mfma_f32_16x16x32_bf16 v[30:33], v[140:143], v[204:207], v[30:33]
	v_mfma_f32_16x16x32_bf16 v[26:29], v[148:151], v[204:207], v[26:29]
	v_mfma_f32_16x16x32_bf16 v[14:17], v[140:143], v[222:225], v[14:17]
	v_mfma_f32_16x16x32_bf16 v[10:13], v[148:151], v[222:225], v[10:13]
	v_mfma_f32_16x16x32_bf16 v[62:65], v[144:147], v[192:195], v[62:65]
	v_mfma_f32_16x16x32_bf16 v[58:61], v[152:155], v[192:195], v[58:61]
	v_mfma_f32_16x16x32_bf16 v[46:49], v[144:147], v[200:203], v[46:49]
	v_mfma_f32_16x16x32_bf16 v[42:45], v[152:155], v[200:203], v[42:45]
	v_mfma_f32_16x16x32_bf16 v[30:33], v[144:147], v[218:221], v[30:33]
	v_mfma_f32_16x16x32_bf16 v[26:29], v[152:155], v[218:221], v[26:29]
	v_mfma_f32_16x16x32_bf16 v[14:17], v[144:147], v[226:229], v[14:17]
	v_mfma_f32_16x16x32_bf16 v[10:13], v[152:155], v[226:229], v[10:13]
	v_mfma_f32_16x16x32_bf16 v[54:57], v[156:159], v[188:191], v[54:57]
	v_mfma_f32_16x16x32_bf16 v[50:53], v[170:173], v[188:191], v[50:53]
	v_mfma_f32_16x16x32_bf16 v[38:41], v[156:159], v[196:199], v[38:41]
	v_mfma_f32_16x16x32_bf16 v[34:37], v[170:173], v[196:199], v[34:37]
	v_mfma_f32_16x16x32_bf16 v[22:25], v[156:159], v[204:207], v[22:25]
	v_mfma_f32_16x16x32_bf16 v[18:21], v[170:173], v[204:207], v[18:21]
	v_mfma_f32_16x16x32_bf16 v[6:9], v[156:159], v[222:225], v[6:9]
	v_mfma_f32_16x16x32_bf16 v[2:5], v[170:173], v[222:225], v[2:5]
	v_mfma_f32_16x16x32_bf16 v[54:57], v[166:169], v[192:195], v[54:57]
	v_mfma_f32_16x16x32_bf16 v[50:53], v[174:177], v[192:195], v[50:53]
	v_mfma_f32_16x16x32_bf16 v[38:41], v[166:169], v[200:203], v[38:41]
	v_mfma_f32_16x16x32_bf16 v[34:37], v[174:177], v[200:203], v[34:37]
	v_mfma_f32_16x16x32_bf16 v[22:25], v[166:169], v[218:221], v[22:25]
	v_mfma_f32_16x16x32_bf16 v[18:21], v[174:177], v[218:221], v[18:21]
	v_mfma_f32_16x16x32_bf16 v[6:9], v[166:169], v[226:229], v[6:9]
	v_mfma_f32_16x16x32_bf16 v[2:5], v[174:177], v[226:229], v[2:5]
	s_barrier
	s_add_i32 s57, s57, 2
	s_add_u32 s20, s20, 0x100
	s_addc_u32 s21, s21, 0
	s_add_u32 s47, s47, 0x100
	s_addc_u32 s56, s56, 0
	s_cmpk_gt_u32 s57, 0x7d
	s_cbranch_scc0 .LBB0_1024
	s_and_b64 vcc, exec, s[10:11]
	s_mov_b32 s45, 0xa000
	s_cbranch_vccz .LBB0_1027
	s_barrier

.LBB0_1046:
	s_add_u32 s3, s18, 0xffe00080
	s_addc_u32 s20, s19, -1
	s_add_i32 s42, 0, 0x10000
	s_cmpk_eq_i32 s47, 0x7c
	s_cselect_b32 s23, s13, s20
	s_cselect_b32 s22, s41, s3
	s_cselect_b32 s21, s11, s46
	s_cselect_b32 s20, s44, s45
	s_add_i32 s3, 0, 0x14000
	v_add_u32_e32 v152, s42, v163
	v_add_u32_e32 v160, s3, v163
	ds_read_b128 v[140:143], v152
	ds_read_b128 v[144:147], v152 offset:1024
	ds_read_b128 v[148:151], v152 offset:2048
	ds_read_b128 v[152:155], v152 offset:3072
	ds_read_b128 v[156:159], v160
	ds_read_b128 v[166:169], v160 offset:1024
	ds_read_b128 v[170:173], v160 offset:2048
	ds_read_b128 v[174:177], v160 offset:3072
	v_lshl_add_u64 v[160:161], s[18:19], 0, v[136:137]
	s_add_i32 m0, s25, 0xc000
	ds_read_b128 v[188:191], v165
	ds_read_b128 v[192:195], v165 offset:1024
	ds_read_b128 v[196:199], v165 offset:2048
	ds_read_b128 v[200:203], v165 offset:3072
	ds_read_b128 v[204:207], v165 offset:4096
	ds_read_b128 v[218:221], v165 offset:5120
	ds_read_b128 v[222:225], v165 offset:6144
	ds_read_b128 v[226:229], v165 offset:7168
	global_load_lds_dwordx4 v[160:161], off
	v_lshl_add_u64 v[160:161], s[18:19], 0, v[138:139]
	s_add_i32 m0, s25, 0xe000
	s_nop 0
	global_load_lds_dwordx4 v[160:161], off
	s_waitcnt vmcnt(8)
	s_waitcnt lgkmcnt(0)
	s_waitcnt lgkmcnt(0)
	v_mfma_f32_16x16x32_bf16 v[126:129], v[140:143], v[188:191], v[126:129]
	v_mfma_f32_16x16x32_bf16 v[122:125], v[148:151], v[188:191], v[122:125]
	s_barrier
	v_mfma_f32_16x16x32_bf16 v[110:113], v[140:143], v[196:199], v[110:113]
	v_mfma_f32_16x16x32_bf16 v[106:109], v[148:151], v[196:199], v[106:109]
	v_mfma_f32_16x16x32_bf16 v[94:97], v[140:143], v[204:207], v[94:97]
	v_mfma_f32_16x16x32_bf16 v[90:93], v[148:151], v[204:207], v[90:93]
	v_mfma_f32_16x16x32_bf16 v[78:81], v[140:143], v[222:225], v[78:81]
	v_mfma_f32_16x16x32_bf16 v[74:77], v[148:151], v[222:225], v[74:77]
	v_mfma_f32_16x16x32_bf16 v[126:129], v[144:147], v[192:195], v[126:129]
	v_mfma_f32_16x16x32_bf16 v[122:125], v[152:155], v[192:195], v[122:125]
	v_mfma_f32_16x16x32_bf16 v[110:113], v[144:147], v[200:203], v[110:113]
	v_mfma_f32_16x16x32_bf16 v[106:109], v[152:155], v[200:203], v[106:109]
	v_mfma_f32_16x16x32_bf16 v[94:97], v[144:147], v[218:221], v[94:97]
	v_mfma_f32_16x16x32_bf16 v[90:93], v[152:155], v[218:221], v[90:93]
	v_mfma_f32_16x16x32_bf16 v[78:81], v[144:147], v[226:229], v[78:81]
	v_mfma_f32_16x16x32_bf16 v[74:77], v[152:155], v[226:229], v[74:77]
	v_mfma_f32_16x16x32_bf16 v[118:121], v[156:159], v[188:191], v[118:121]
	v_mfma_f32_16x16x32_bf16 v[114:117], v[170:173], v[188:191], v[114:117]
	v_mfma_f32_16x16x32_bf16 v[102:105], v[156:159], v[196:199], v[102:105]
	v_mfma_f32_16x16x32_bf16 v[98:101], v[170:173], v[196:199], v[98:101]
	v_mfma_f32_16x16x32_bf16 v[86:89], v[156:159], v[204:207], v[86:89]
	v_mfma_f32_16x16x32_bf16 v[82:85], v[170:173], v[204:207], v[82:85]
	v_mfma_f32_16x16x32_bf16 v[70:73], v[156:159], v[222:225], v[70:73]
	v_mfma_f32_16x16x32_bf16 v[66:69], v[170:173], v[222:225], v[66:69]
	v_mfma_f32_16x16x32_bf16 v[118:121], v[166:169], v[192:195], v[118:121]
	v_mfma_f32_16x16x32_bf16 v[114:117], v[174:177], v[192:195], v[114:117]
	v_mfma_f32_16x16x32_bf16 v[102:105], v[166:169], v[200:203], v[102:105]
	v_mfma_f32_16x16x32_bf16 v[98:101], v[174:177], v[200:203], v[98:101]
	v_mfma_f32_16x16x32_bf16 v[86:89], v[166:169], v[218:221], v[86:89]
	v_mfma_f32_16x16x32_bf16 v[82:85], v[174:177], v[218:221], v[82:85]
	v_mfma_f32_16x16x32_bf16 v[70:73], v[166:169], v[226:229], v[70:73]
	v_mfma_f32_16x16x32_bf16 v[66:69], v[174:177], v[226:229], v[66:69]
	s_barrier
	s_add_i32 s42, s42, s24
	v_lshl_add_u64 v[160:161], s[20:21], 0, v[0:1]
	s_mov_b32 m0, s42
	ds_read_b128 v[188:191], v165 offset:16384
	ds_read_b128 v[192:195], v165 offset:17408
	ds_read_b128 v[196:199], v165 offset:18432
	ds_read_b128 v[200:203], v165 offset:19456
	ds_read_b128 v[204:207], v165 offset:20480
	ds_read_b128 v[218:221], v165 offset:21504
	ds_read_b128 v[222:225], v165 offset:22528
	ds_read_b128 v[226:229], v165 offset:23552
	global_load_lds_dwordx4 v[160:161], off
	s_add_i32 m0, s42, 0x2000
	s_add_u32 s56, s20, 0x200000
	v_lshl_add_u64 v[178:179], s[20:21], 0, v[130:131]
	s_addc_u32 s57, s21, 0
	s_add_i32 s3, s3, s24
	global_load_lds_dwordx4 v[178:179], off
	v_lshl_add_u64 v[180:181], s[56:57], 0, v[0:1]
	s_mov_b32 m0, s3
	v_lshl_add_u64 v[182:183], s[22:23], 0, v[132:133]
	global_load_lds_dwordx4 v[180:181], off
	v_lshl_add_u64 v[180:181], s[56:57], 0, v[130:131]
	s_add_i32 m0, s3, 0x2000
	s_nop 0
	global_load_lds_dwordx4 v[180:181], off
	v_lshl_add_u64 v[180:181], s[22:23], 0, v[134:135]
	s_mov_b32 m0, s25
	s_nop 0
	global_load_lds_dwordx4 v[180:181], off
	s_mov_b32 m0, s27
	s_nop 0
	global_load_lds_dwordx4 v[182:183], off
	s_waitcnt vmcnt(8)
	s_waitcnt lgkmcnt(0)
	s_waitcnt lgkmcnt(0)
	v_mfma_f32_16x16x32_bf16 v[62:65], v[140:143], v[188:191], v[62:65]
	v_mfma_f32_16x16x32_bf16 v[58:61], v[148:151], v[188:191], v[58:61]
	s_barrier
	v_mfma_f32_16x16x32_bf16 v[46:49], v[140:143], v[196:199], v[46:49]
	v_mfma_f32_16x16x32_bf16 v[42:45], v[148:151], v[196:199], v[42:45]
	v_mfma_f32_16x16x32_bf16 v[30:33], v[140:143], v[204:207], v[30:33]
	v_mfma_f32_16x16x32_bf16 v[26:29], v[148:151], v[204:207], v[26:29]
	v_mfma_f32_16x16x32_bf16 v[14:17], v[140:143], v[222:225], v[14:17]
	v_mfma_f32_16x16x32_bf16 v[10:13], v[148:151], v[222:225], v[10:13]
	v_mfma_f32_16x16x32_bf16 v[62:65], v[144:147], v[192:195], v[62:65]
	v_mfma_f32_16x16x32_bf16 v[58:61], v[152:155], v[192:195], v[58:61]
	v_mfma_f32_16x16x32_bf16 v[46:49], v[144:147], v[200:203], v[46:49]
	v_mfma_f32_16x16x32_bf16 v[42:45], v[152:155], v[200:203], v[42:45]
	v_mfma_f32_16x16x32_bf16 v[30:33], v[144:147], v[218:221], v[30:33]
	v_mfma_f32_16x16x32_bf16 v[26:29], v[152:155], v[218:221], v[26:29]
	v_mfma_f32_16x16x32_bf16 v[14:17], v[144:147], v[226:229], v[14:17]
	v_mfma_f32_16x16x32_bf16 v[10:13], v[152:155], v[226:229], v[10:13]
	v_mfma_f32_16x16x32_bf16 v[54:57], v[156:159], v[188:191], v[54:57]
	v_mfma_f32_16x16x32_bf16 v[50:53], v[170:173], v[188:191], v[50:53]
	v_mfma_f32_16x16x32_bf16 v[38:41], v[156:159], v[196:199], v[38:41]
	v_mfma_f32_16x16x32_bf16 v[34:37], v[170:173], v[196:199], v[34:37]
	v_mfma_f32_16x16x32_bf16 v[22:25], v[156:159], v[204:207], v[22:25]
	v_mfma_f32_16x16x32_bf16 v[18:21], v[170:173], v[204:207], v[18:21]
	v_mfma_f32_16x16x32_bf16 v[6:9], v[156:159], v[222:225], v[6:9]
	v_mfma_f32_16x16x32_bf16 v[2:5], v[170:173], v[222:225], v[2:5]
	v_mfma_f32_16x16x32_bf16 v[54:57], v[166:169], v[192:195], v[54:57]
	v_mfma_f32_16x16x32_bf16 v[50:53], v[174:177], v[192:195], v[50:53]
	v_mfma_f32_16x16x32_bf16 v[38:41], v[166:169], v[200:203], v[38:41]
	v_mfma_f32_16x16x32_bf16 v[34:37], v[174:177], v[200:203], v[34:37]
	v_mfma_f32_16x16x32_bf16 v[22:25], v[166:169], v[218:221], v[22:25]
	v_mfma_f32_16x16x32_bf16 v[18:21], v[174:177], v[218:221], v[18:21]
	v_mfma_f32_16x16x32_bf16 v[6:9], v[166:169], v[226:229], v[6:9]
	v_mfma_f32_16x16x32_bf16 v[2:5], v[174:177], v[226:229], v[2:5]
	s_barrier
	s_add_i32 s3, 0, 0x18000
	s_add_i32 s42, 0, 0x1c000
	v_add_u32_e32 v152, s3, v163
	v_add_u32_e32 v174, s42, v163
	ds_read_b128 v[140:143], v152
	ds_read_b128 v[144:147], v152 offset:1024
	ds_read_b128 v[148:151], v152 offset:2048
	ds_read_b128 v[152:155], v152 offset:3072
	ds_read_b128 v[156:159], v174
	ds_read_b128 v[166:169], v174 offset:1024
	ds_read_b128 v[170:173], v174 offset:2048
	ds_read_b128 v[174:177], v174 offset:3072
	s_add_u32 s22, s22, 0x200000
	s_addc_u32 s23, s23, 0
	s_mov_b32 m0, s28
	v_lshl_add_u64 v[184:185], s[22:23], 0, v[134:135]
	ds_read_b128 v[188:191], v165 offset:32768
	ds_read_b128 v[192:195], v165 offset:33792
	ds_read_b128 v[196:199], v165 offset:34816
	ds_read_b128 v[200:203], v165 offset:35840
	ds_read_b128 v[204:207], v165 offset:36864
	ds_read_b128 v[218:221], v165 offset:37888
	ds_read_b128 v[222:225], v165 offset:38912
	ds_read_b128 v[226:229], v165 offset:39936
	global_load_lds_dwordx4 v[184:185], off
	v_lshl_add_u64 v[184:185], s[22:23], 0, v[132:133]
	s_mov_b32 m0, s29
	s_nop 0
	global_load_lds_dwordx4 v[184:185], off
	s_waitcnt vmcnt(8)
	s_waitcnt lgkmcnt(0)
	s_waitcnt lgkmcnt(0)
	v_mfma_f32_16x16x32_bf16 v[126:129], v[140:143], v[188:191], v[126:129]
	v_mfma_f32_16x16x32_bf16 v[122:125], v[148:151], v[188:191], v[122:125]
	s_barrier
	v_mfma_f32_16x16x32_bf16 v[110:113], v[140:143], v[196:199], v[110:113]
	v_mfma_f32_16x16x32_bf16 v[106:109], v[148:151], v[196:199], v[106:109]
	v_mfma_f32_16x16x32_bf16 v[94:97], v[140:143], v[204:207], v[94:97]
	v_mfma_f32_16x16x32_bf16 v[90:93], v[148:151], v[204:207], v[90:93]
	v_mfma_f32_16x16x32_bf16 v[78:81], v[140:143], v[222:225], v[78:81]
	v_mfma_f32_16x16x32_bf16 v[74:77], v[148:151], v[222:225], v[74:77]
	v_mfma_f32_16x16x32_bf16 v[126:129], v[144:147], v[192:195], v[126:129]
	v_mfma_f32_16x16x32_bf16 v[122:125], v[152:155], v[192:195], v[122:125]
	v_mfma_f32_16x16x32_bf16 v[110:113], v[144:147], v[200:203], v[110:113]
	v_mfma_f32_16x16x32_bf16 v[106:109], v[152:155], v[200:203], v[106:109]
	v_mfma_f32_16x16x32_bf16 v[94:97], v[144:147], v[218:221], v[94:97]
	v_mfma_f32_16x16x32_bf16 v[90:93], v[152:155], v[218:221], v[90:93]
	v_mfma_f32_16x16x32_bf16 v[78:81], v[144:147], v[226:229], v[78:81]
	v_mfma_f32_16x16x32_bf16 v[74:77], v[152:155], v[226:229], v[74:77]
	v_mfma_f32_16x16x32_bf16 v[118:121], v[156:159], v[188:191], v[118:121]
	v_mfma_f32_16x16x32_bf16 v[114:117], v[170:173], v[188:191], v[114:117]
	v_mfma_f32_16x16x32_bf16 v[102:105], v[156:159], v[196:199], v[102:105]
	v_mfma_f32_16x16x32_bf16 v[98:101], v[170:173], v[196:199], v[98:101]
	v_mfma_f32_16x16x32_bf16 v[86:89], v[156:159], v[204:207], v[86:89]
	v_mfma_f32_16x16x32_bf16 v[82:85], v[170:173], v[204:207], v[82:85]
	v_mfma_f32_16x16x32_bf16 v[70:73], v[156:159], v[222:225], v[70:73]
	v_mfma_f32_16x16x32_bf16 v[66:69], v[170:173], v[222:225], v[66:69]
	v_mfma_f32_16x16x32_bf16 v[118:121], v[166:169], v[192:195], v[118:121]
	v_mfma_f32_16x16x32_bf16 v[114:117], v[174:177], v[192:195], v[114:117]
	v_mfma_f32_16x16x32_bf16 v[102:105], v[166:169], v[200:203], v[102:105]
	v_mfma_f32_16x16x32_bf16 v[98:101], v[174:177], v[200:203], v[98:101]
	v_mfma_f32_16x16x32_bf16 v[86:89], v[166:169], v[218:221], v[86:89]
	v_mfma_f32_16x16x32_bf16 v[82:85], v[174:177], v[218:221], v[82:85]
	v_mfma_f32_16x16x32_bf16 v[70:73], v[166:169], v[226:229], v[70:73]
	v_mfma_f32_16x16x32_bf16 v[66:69], v[174:177], v[226:229], v[66:69]
	s_barrier
	s_add_i32 s3, s3, s24
	v_lshl_add_u64 v[160:161], v[160:161], 0, s[52:53]
	s_mov_b32 m0, s3
	ds_read_b128 v[188:191], v165 offset:49152
	ds_read_b128 v[192:195], v165 offset:50176
	ds_read_b128 v[196:199], v165 offset:51200
	ds_read_b128 v[200:203], v165 offset:52224
	ds_read_b128 v[204:207], v165 offset:53248
	ds_read_b128 v[218:221], v165 offset:54272
	ds_read_b128 v[222:225], v165 offset:55296
	ds_read_b128 v[226:229], v165 offset:56320
	global_load_lds_dwordx4 v[160:161], off
	s_add_i32 m0, s3, 0x2000
	s_add_u32 s20, s20, 0x200080
	v_lshl_add_u64 v[160:161], v[178:179], 0, s[52:53]
	s_addc_u32 s21, s21, 0
	s_add_i32 s3, s42, s24
	global_load_lds_dwordx4 v[160:161], off
	v_lshl_add_u64 v[160:161], s[20:21], 0, v[0:1]
	s_mov_b32 m0, s3
	s_nop 0
	global_load_lds_dwordx4 v[160:161], off
	v_lshl_add_u64 v[160:161], s[20:21], 0, v[130:131]
	s_add_i32 m0, s3, 0x2000
	s_nop 0
	global_load_lds_dwordx4 v[160:161], off
	v_lshl_add_u64 v[160:161], v[180:181], 0, s[52:53]
	s_mov_b32 m0, s30
	s_nop 0
	global_load_lds_dwordx4 v[160:161], off
	v_lshl_add_u64 v[160:161], v[182:183], 0, s[52:53]
	s_mov_b32 m0, s31
	s_nop 0
	global_load_lds_dwordx4 v[160:161], off
	s_waitcnt vmcnt(8)
	s_waitcnt lgkmcnt(0)
	s_waitcnt lgkmcnt(0)
	v_mfma_f32_16x16x32_bf16 v[62:65], v[140:143], v[188:191], v[62:65]
	v_mfma_f32_16x16x32_bf16 v[58:61], v[148:151], v[188:191], v[58:61]
	s_barrier
	v_mfma_f32_16x16x32_bf16 v[46:49], v[140:143], v[196:199], v[46:49]
	v_mfma_f32_16x16x32_bf16 v[42:45], v[148:151], v[196:199], v[42:45]
	v_mfma_f32_16x16x32_bf16 v[30:33], v[140:143], v[204:207], v[30:33]
	v_mfma_f32_16x16x32_bf16 v[26:29], v[148:151], v[204:207], v[26:29]
	v_mfma_f32_16x16x32_bf16 v[14:17], v[140:143], v[222:225], v[14:17]
	v_mfma_f32_16x16x32_bf16 v[10:13], v[148:151], v[222:225], v[10:13]
	v_mfma_f32_16x16x32_bf16 v[62:65], v[144:147], v[192:195], v[62:65]
	v_mfma_f32_16x16x32_bf16 v[58:61], v[152:155], v[192:195], v[58:61]
	v_mfma_f32_16x16x32_bf16 v[46:49], v[144:147], v[200:203], v[46:49]
	v_mfma_f32_16x16x32_bf16 v[42:45], v[152:155], v[200:203], v[42:45]
	v_mfma_f32_16x16x32_bf16 v[30:33], v[144:147], v[218:221], v[30:33]
	v_mfma_f32_16x16x32_bf16 v[26:29], v[152:155], v[218:221], v[26:29]
	v_mfma_f32_16x16x32_bf16 v[14:17], v[144:147], v[226:229], v[14:17]
	v_mfma_f32_16x16x32_bf16 v[10:13], v[152:155], v[226:229], v[10:13]
	v_mfma_f32_16x16x32_bf16 v[54:57], v[156:159], v[188:191], v[54:57]
	v_mfma_f32_16x16x32_bf16 v[50:53], v[170:173], v[188:191], v[50:53]
	v_mfma_f32_16x16x32_bf16 v[38:41], v[156:159], v[196:199], v[38:41]
	v_mfma_f32_16x16x32_bf16 v[34:37], v[170:173], v[196:199], v[34:37]
	v_mfma_f32_16x16x32_bf16 v[22:25], v[156:159], v[204:207], v[22:25]
	v_mfma_f32_16x16x32_bf16 v[18:21], v[170:173], v[204:207], v[18:21]
	v_mfma_f32_16x16x32_bf16 v[6:9], v[156:159], v[222:225], v[6:9]
	v_mfma_f32_16x16x32_bf16 v[2:5], v[170:173], v[222:225], v[2:5]
	v_mfma_f32_16x16x32_bf16 v[54:57], v[166:169], v[192:195], v[54:57]
	v_mfma_f32_16x16x32_bf16 v[50:53], v[174:177], v[192:195], v[50:53]
	v_mfma_f32_16x16x32_bf16 v[38:41], v[166:169], v[200:203], v[38:41]
	v_mfma_f32_16x16x32_bf16 v[34:37], v[174:177], v[200:203], v[34:37]
	v_mfma_f32_16x16x32_bf16 v[22:25], v[166:169], v[218:221], v[22:25]
	v_mfma_f32_16x16x32_bf16 v[18:21], v[174:177], v[218:221], v[18:21]
	v_mfma_f32_16x16x32_bf16 v[6:9], v[166:169], v[226:229], v[6:9]
	v_mfma_f32_16x16x32_bf16 v[2:5], v[174:177], v[226:229], v[2:5]
	s_barrier
	s_add_i32 s47, s47, 2
	s_add_u32 s18, s18, 0x100
	s_addc_u32 s19, s19, 0
	s_add_u32 s45, s45, 0x100
	s_addc_u32 s46, s46, 0
	s_cmpk_gt_u32 s47, 0x7d
	s_cbranch_scc0 .LBB0_1046
	s_and_b64 vcc, exec, s[8:9]
	s_movk_i32 s41, 0x6000
	s_mov_b32 s44, 0x8000
	s_mov_b32 s45, 0xa000
	s_cbranch_vccz .LBB0_1049
	s_barrier
